# merge-gate sigmoid epilogues: -log2(e) folded into the 8 row scales (128 fewer VALU per tile)
# speedup vs baseline: 1.0016x; 1.0016x over previous
.LBB0_670:
	s_add_u32 s40, s38, 0xfffc0080
	s_addc_u32 s41, s39, -1
	s_add_i32 s54, 0, 0x10000
	v_add_u32_e32 v140, s54, v145
	ds_read_b128 v[154:157], v140
	ds_read_b128 v[158:161], v140 offset:1024
	ds_read_b128 v[162:165], v140 offset:2048
	ds_read_b128 v[166:169], v140 offset:3072
	s_cmp_eq_u32 s53, 12
	s_cselect_b32 s43, s11, s41
	s_cselect_b32 s42, s17, s40
	s_cselect_b32 s41, s23, s52
	s_cselect_b32 s40, s44, s45
	v_lshl_add_u64 v[142:143], s[38:39], 0, v[136:137]
	s_add_i32 m0, s21, 0xc000
	ds_read_b128 v[170:173], v153
	ds_read_b128 v[174:177], v153 offset:1024
	ds_read_b128 v[188:191], v153 offset:2048
	ds_read_b128 v[192:195], v153 offset:3072
	ds_read_b128 v[196:199], v153 offset:4096
	ds_read_b128 v[200:203], v153 offset:5120
	ds_read_b128 v[204:207], v153 offset:6144
	ds_read_b128 v[208:211], v153 offset:7168
	global_load_lds_dwordx4 v[142:143], off
	v_lshl_add_u64 v[142:143], s[38:39], 0, v[138:139]
	s_add_i32 m0, s21, 0xe000
	s_nop 0
	global_load_lds_dwordx4 v[142:143], off
	s_waitcnt lgkmcnt(8)
	s_barrier
	s_waitcnt lgkmcnt(0)
	s_setprio 1
	s_waitcnt lgkmcnt(0)
	v_mfma_f32_16x16x32_bf16 v[126:129], v[154:157], v[170:173], v[126:129]
	v_mfma_f32_16x16x32_bf16 v[122:125], v[162:165], v[170:173], v[122:125]
	v_mfma_f32_16x16x32_bf16 v[118:121], v[154:157], v[188:191], v[118:121]
	v_mfma_f32_16x16x32_bf16 v[110:113], v[162:165], v[188:191], v[110:113]
	v_mfma_f32_16x16x32_bf16 v[102:105], v[154:157], v[196:199], v[102:105]
	v_mfma_f32_16x16x32_bf16 v[94:97], v[162:165], v[196:199], v[94:97]
	v_mfma_f32_16x16x32_bf16 v[86:89], v[154:157], v[204:207], v[86:89]
	v_mfma_f32_16x16x32_bf16 v[78:81], v[162:165], v[204:207], v[78:81]
	v_mfma_f32_16x16x32_bf16 v[126:129], v[158:161], v[174:177], v[126:129]
	v_mfma_f32_16x16x32_bf16 v[122:125], v[166:169], v[174:177], v[122:125]
	v_mfma_f32_16x16x32_bf16 v[118:121], v[158:161], v[192:195], v[118:121]
	v_mfma_f32_16x16x32_bf16 v[110:113], v[166:169], v[192:195], v[110:113]
	v_mfma_f32_16x16x32_bf16 v[102:105], v[158:161], v[200:203], v[102:105]
	v_mfma_f32_16x16x32_bf16 v[94:97], v[166:169], v[200:203], v[94:97]
	v_mfma_f32_16x16x32_bf16 v[86:89], v[158:161], v[208:211], v[86:89]
	v_mfma_f32_16x16x32_bf16 v[78:81], v[166:169], v[208:211], v[78:81]
	s_setprio 0
	s_barrier
	s_add_i32 s56, 0, 0x14000
	s_add_i32 s54, s54, s20
	v_add_u32_e32 v140, s56, v145
	v_lshl_add_u64 v[142:143], s[40:41], 0, v[16:17]
	s_mov_b32 m0, s54
	ds_read_b128 v[212:215], v140
	ds_read_b128 v[216:219], v140 offset:1024
	ds_read_b128 v[220:223], v140 offset:2048
	ds_read_b128 v[224:227], v140 offset:3072
	global_load_lds_dwordx4 v[142:143], off
	v_lshl_add_u64 v[146:147], s[40:41], 0, v[134:135]
	s_add_i32 m0, s54, 0x2000
	s_nop 0
	global_load_lds_dwordx4 v[146:147], off
	s_barrier
	s_waitcnt lgkmcnt(0)
	s_setprio 1
	s_waitcnt lgkmcnt(0)
	v_mfma_f32_16x16x32_bf16 v[114:117], v[212:215], v[170:173], v[114:117]
	v_mfma_f32_16x16x32_bf16 v[106:109], v[220:223], v[170:173], v[106:109]
	v_mfma_f32_16x16x32_bf16 v[98:101], v[212:215], v[188:191], v[98:101]
	v_mfma_f32_16x16x32_bf16 v[90:93], v[220:223], v[188:191], v[90:93]
	v_mfma_f32_16x16x32_bf16 v[82:85], v[212:215], v[196:199], v[82:85]
	v_mfma_f32_16x16x32_bf16 v[74:77], v[220:223], v[196:199], v[74:77]
	v_mfma_f32_16x16x32_bf16 v[70:73], v[212:215], v[204:207], v[70:73]
	v_mfma_f32_16x16x32_bf16 v[66:69], v[220:223], v[204:207], v[66:69]
	v_mfma_f32_16x16x32_bf16 v[114:117], v[216:219], v[174:177], v[114:117]
	v_mfma_f32_16x16x32_bf16 v[106:109], v[224:227], v[174:177], v[106:109]
	v_mfma_f32_16x16x32_bf16 v[98:101], v[216:219], v[192:195], v[98:101]
	v_mfma_f32_16x16x32_bf16 v[90:93], v[224:227], v[192:195], v[90:93]
	v_mfma_f32_16x16x32_bf16 v[82:85], v[216:219], v[200:203], v[82:85]
	v_mfma_f32_16x16x32_bf16 v[74:77], v[224:227], v[200:203], v[74:77]
	v_mfma_f32_16x16x32_bf16 v[70:73], v[216:219], v[208:211], v[70:73]
	v_mfma_f32_16x16x32_bf16 v[66:69], v[224:227], v[208:211], v[66:69]
	s_setprio 0
	s_mov_b32 m0, s21
	v_lshl_add_u64 v[150:151], s[42:43], 0, v[130:131]
	s_barrier
	ds_read_b128 v[170:173], v153 offset:16384
	ds_read_b128 v[174:177], v153 offset:17408
	ds_read_b128 v[188:191], v153 offset:18432
	ds_read_b128 v[192:195], v153 offset:19456
	ds_read_b128 v[196:199], v153 offset:20480
	ds_read_b128 v[200:203], v153 offset:21504
	ds_read_b128 v[204:207], v153 offset:22528
	ds_read_b128 v[208:211], v153 offset:23552
	global_load_lds_dwordx4 v[150:151], off
	v_lshl_add_u64 v[178:179], s[42:43], 0, v[132:133]
	s_mov_b32 m0, s25
	s_nop 0
	global_load_lds_dwordx4 v[178:179], off
	s_barrier
	s_waitcnt lgkmcnt(0)
	s_setprio 1
	s_waitcnt lgkmcnt(0)
	v_mfma_f32_16x16x32_bf16 v[62:65], v[154:157], v[170:173], v[62:65]
	v_mfma_f32_16x16x32_bf16 v[58:61], v[162:165], v[170:173], v[58:61]
	v_mfma_f32_16x16x32_bf16 v[54:57], v[154:157], v[188:191], v[54:57]
	v_mfma_f32_16x16x32_bf16 v[46:49], v[162:165], v[188:191], v[46:49]
	v_mfma_f32_16x16x32_bf16 v[38:41], v[154:157], v[196:199], v[38:41]
	v_mfma_f32_16x16x32_bf16 v[30:33], v[162:165], v[196:199], v[30:33]
	v_mfma_f32_16x16x32_bf16 v[22:25], v[154:157], v[204:207], v[22:25]
	v_mfma_f32_16x16x32_bf16 v[12:15], v[162:165], v[204:207], v[12:15]
	v_mfma_f32_16x16x32_bf16 v[62:65], v[158:161], v[174:177], v[62:65]
	v_mfma_f32_16x16x32_bf16 v[58:61], v[166:169], v[174:177], v[58:61]
	v_mfma_f32_16x16x32_bf16 v[54:57], v[158:161], v[192:195], v[54:57]
	v_mfma_f32_16x16x32_bf16 v[46:49], v[166:169], v[192:195], v[46:49]
	v_mfma_f32_16x16x32_bf16 v[38:41], v[158:161], v[200:203], v[38:41]
	v_mfma_f32_16x16x32_bf16 v[30:33], v[166:169], v[200:203], v[30:33]
	v_mfma_f32_16x16x32_bf16 v[22:25], v[158:161], v[208:211], v[22:25]
	v_mfma_f32_16x16x32_bf16 v[12:15], v[166:169], v[208:211], v[12:15]
	s_setprio 0
	s_barrier
	s_add_u32 s54, s40, 0x40000
	s_addc_u32 s55, s41, 0
	s_add_i32 s56, s56, s20
	v_lshl_add_u64 v[154:155], s[54:55], 0, v[16:17]
	s_mov_b32 m0, s56
	s_nop 0
	global_load_lds_dwordx4 v[154:155], off
	v_lshl_add_u64 v[154:155], s[54:55], 0, v[134:135]
	s_add_i32 m0, s56, 0x2000
	s_nop 0
	global_load_lds_dwordx4 v[154:155], off
	s_waitcnt vmcnt(6)
	s_barrier
	s_setprio 1
	v_mfma_f32_16x16x32_bf16 v[50:53], v[212:215], v[170:173], v[50:53]
	v_mfma_f32_16x16x32_bf16 v[42:45], v[220:223], v[170:173], v[42:45]
	v_mfma_f32_16x16x32_bf16 v[34:37], v[212:215], v[188:191], v[34:37]
	v_mfma_f32_16x16x32_bf16 v[26:29], v[220:223], v[188:191], v[26:29]
	v_mfma_f32_16x16x32_bf16 v[18:21], v[212:215], v[196:199], v[18:21]
	v_mfma_f32_16x16x32_bf16 v[8:11], v[220:223], v[196:199], v[8:11]
	v_mfma_f32_16x16x32_bf16 v[4:7], v[212:215], v[204:207], v[4:7]
	v_mfma_f32_16x16x32_bf16 v[0:3], v[220:223], v[204:207], v[0:3]
	v_mfma_f32_16x16x32_bf16 v[50:53], v[216:219], v[174:177], v[50:53]
	v_mfma_f32_16x16x32_bf16 v[42:45], v[224:227], v[174:177], v[42:45]
	v_mfma_f32_16x16x32_bf16 v[34:37], v[216:219], v[192:195], v[34:37]
	v_mfma_f32_16x16x32_bf16 v[26:29], v[224:227], v[192:195], v[26:29]
	v_mfma_f32_16x16x32_bf16 v[18:21], v[216:219], v[200:203], v[18:21]
	v_mfma_f32_16x16x32_bf16 v[8:11], v[224:227], v[200:203], v[8:11]
	v_mfma_f32_16x16x32_bf16 v[4:7], v[216:219], v[208:211], v[4:7]
	v_mfma_f32_16x16x32_bf16 v[0:3], v[224:227], v[208:211], v[0:3]
	s_setprio 0
	s_add_i32 s54, 0, 0x18000
	v_add_u32_e32 v140, s54, v145
	s_barrier
	ds_read_b128 v[154:157], v140
	ds_read_b128 v[158:161], v140 offset:1024
	ds_read_b128 v[162:165], v140 offset:2048
	ds_read_b128 v[166:169], v140 offset:3072
	s_add_u32 s42, s42, 0x40000
	s_addc_u32 s43, s43, 0
	s_mov_b32 m0, s33
	v_lshl_add_u64 v[180:181], s[42:43], 0, v[130:131]
	ds_read_b128 v[170:173], v153 offset:32768
	ds_read_b128 v[174:177], v153 offset:33792
	ds_read_b128 v[188:191], v153 offset:34816
	ds_read_b128 v[192:195], v153 offset:35840
	ds_read_b128 v[196:199], v153 offset:36864
	ds_read_b128 v[200:203], v153 offset:37888
	ds_read_b128 v[204:207], v153 offset:38912
	ds_read_b128 v[208:211], v153 offset:39936
	global_load_lds_dwordx4 v[180:181], off
	v_lshl_add_u64 v[180:181], s[42:43], 0, v[132:133]
	s_mov_b32 m0, s35
	s_nop 0
	global_load_lds_dwordx4 v[180:181], off
	s_waitcnt lgkmcnt(8)
	s_barrier
	s_waitcnt lgkmcnt(0)
	s_setprio 1
	s_waitcnt lgkmcnt(0)
	v_mfma_f32_16x16x32_bf16 v[126:129], v[154:157], v[170:173], v[126:129]
	v_mfma_f32_16x16x32_bf16 v[122:125], v[162:165], v[170:173], v[122:125]
	v_mfma_f32_16x16x32_bf16 v[118:121], v[154:157], v[188:191], v[118:121]
	v_mfma_f32_16x16x32_bf16 v[110:113], v[162:165], v[188:191], v[110:113]
	v_mfma_f32_16x16x32_bf16 v[102:105], v[154:157], v[196:199], v[102:105]
	v_mfma_f32_16x16x32_bf16 v[94:97], v[162:165], v[196:199], v[94:97]
	v_mfma_f32_16x16x32_bf16 v[86:89], v[154:157], v[204:207], v[86:89]
	v_mfma_f32_16x16x32_bf16 v[78:81], v[162:165], v[204:207], v[78:81]
	v_mfma_f32_16x16x32_bf16 v[126:129], v[158:161], v[174:177], v[126:129]
	v_mfma_f32_16x16x32_bf16 v[122:125], v[166:169], v[174:177], v[122:125]
	v_mfma_f32_16x16x32_bf16 v[118:121], v[158:161], v[192:195], v[118:121]
	v_mfma_f32_16x16x32_bf16 v[110:113], v[166:169], v[192:195], v[110:113]
	v_mfma_f32_16x16x32_bf16 v[102:105], v[158:161], v[200:203], v[102:105]
	v_mfma_f32_16x16x32_bf16 v[94:97], v[166:169], v[200:203], v[94:97]
	v_mfma_f32_16x16x32_bf16 v[86:89], v[158:161], v[208:211], v[86:89]
	v_mfma_f32_16x16x32_bf16 v[78:81], v[166:169], v[208:211], v[78:81]
	s_setprio 0
	s_barrier
	s_add_i32 s42, 0, 0x1c000
	s_add_i32 s43, s54, s20
	v_add_u32_e32 v140, s42, v145
	v_lshl_add_u64 v[142:143], v[142:143], 0, s[14:15]
	s_mov_b32 m0, s43
	ds_read_b128 v[212:215], v140
	ds_read_b128 v[216:219], v140 offset:1024
	ds_read_b128 v[220:223], v140 offset:2048
	ds_read_b128 v[224:227], v140 offset:3072
	global_load_lds_dwordx4 v[142:143], off
	v_lshl_add_u64 v[142:143], v[146:147], 0, s[14:15]
	s_add_i32 m0, s43, 0x2000
	s_nop 0
	global_load_lds_dwordx4 v[142:143], off
	s_barrier
	s_waitcnt lgkmcnt(0)
	s_setprio 1
	s_waitcnt lgkmcnt(0)
	v_mfma_f32_16x16x32_bf16 v[114:117], v[212:215], v[170:173], v[114:117]
	v_mfma_f32_16x16x32_bf16 v[106:109], v[220:223], v[170:173], v[106:109]
	v_mfma_f32_16x16x32_bf16 v[98:101], v[212:215], v[188:191], v[98:101]
	v_mfma_f32_16x16x32_bf16 v[90:93], v[220:223], v[188:191], v[90:93]
	v_mfma_f32_16x16x32_bf16 v[82:85], v[212:215], v[196:199], v[82:85]
	v_mfma_f32_16x16x32_bf16 v[74:77], v[220:223], v[196:199], v[74:77]
	v_mfma_f32_16x16x32_bf16 v[70:73], v[212:215], v[204:207], v[70:73]
	v_mfma_f32_16x16x32_bf16 v[66:69], v[220:223], v[204:207], v[66:69]
	v_mfma_f32_16x16x32_bf16 v[114:117], v[216:219], v[174:177], v[114:117]
	v_mfma_f32_16x16x32_bf16 v[106:109], v[224:227], v[174:177], v[106:109]
	v_mfma_f32_16x16x32_bf16 v[98:101], v[216:219], v[192:195], v[98:101]
	v_mfma_f32_16x16x32_bf16 v[90:93], v[224:227], v[192:195], v[90:93]
	v_mfma_f32_16x16x32_bf16 v[82:85], v[216:219], v[200:203], v[82:85]
	v_mfma_f32_16x16x32_bf16 v[74:77], v[224:227], v[200:203], v[74:77]
	v_mfma_f32_16x16x32_bf16 v[70:73], v[216:219], v[208:211], v[70:73]
	v_mfma_f32_16x16x32_bf16 v[66:69], v[224:227], v[208:211], v[66:69]
	s_setprio 0
	s_mov_b32 m0, s46
	v_lshl_add_u64 v[142:143], v[150:151], 0, s[14:15]
	s_barrier
	ds_read_b128 v[170:173], v153 offset:49152
	ds_read_b128 v[174:177], v153 offset:50176
	ds_read_b128 v[188:191], v153 offset:51200
	ds_read_b128 v[192:195], v153 offset:52224
	ds_read_b128 v[196:199], v153 offset:53248
	ds_read_b128 v[200:203], v153 offset:54272
	ds_read_b128 v[204:207], v153 offset:55296
	ds_read_b128 v[208:211], v153 offset:56320
	global_load_lds_dwordx4 v[142:143], off
	v_lshl_add_u64 v[142:143], v[178:179], 0, s[14:15]
	s_mov_b32 m0, s47
	s_nop 0
	global_load_lds_dwordx4 v[142:143], off
	s_barrier
	s_waitcnt lgkmcnt(0)
	s_setprio 1
	s_waitcnt lgkmcnt(0)
	v_mfma_f32_16x16x32_bf16 v[62:65], v[154:157], v[170:173], v[62:65]
	v_mfma_f32_16x16x32_bf16 v[58:61], v[162:165], v[170:173], v[58:61]
	v_mfma_f32_16x16x32_bf16 v[54:57], v[154:157], v[188:191], v[54:57]
	v_mfma_f32_16x16x32_bf16 v[46:49], v[162:165], v[188:191], v[46:49]
	v_mfma_f32_16x16x32_bf16 v[38:41], v[154:157], v[196:199], v[38:41]
	v_mfma_f32_16x16x32_bf16 v[30:33], v[162:165], v[196:199], v[30:33]
	v_mfma_f32_16x16x32_bf16 v[22:25], v[154:157], v[204:207], v[22:25]
	v_mfma_f32_16x16x32_bf16 v[12:15], v[162:165], v[204:207], v[12:15]
	v_mfma_f32_16x16x32_bf16 v[62:65], v[158:161], v[174:177], v[62:65]
	v_mfma_f32_16x16x32_bf16 v[58:61], v[166:169], v[174:177], v[58:61]
	v_mfma_f32_16x16x32_bf16 v[54:57], v[158:161], v[192:195], v[54:57]
	v_mfma_f32_16x16x32_bf16 v[46:49], v[166:169], v[192:195], v[46:49]
	v_mfma_f32_16x16x32_bf16 v[38:41], v[158:161], v[200:203], v[38:41]
	v_mfma_f32_16x16x32_bf16 v[30:33], v[166:169], v[200:203], v[30:33]
	v_mfma_f32_16x16x32_bf16 v[22:25], v[158:161], v[208:211], v[22:25]
	v_mfma_f32_16x16x32_bf16 v[12:15], v[166:169], v[208:211], v[12:15]
	s_setprio 0
	s_barrier
	s_add_u32 s40, s40, 0x40080
	s_addc_u32 s41, s41, 0
	s_add_i32 s42, s42, s20
	v_lshl_add_u64 v[142:143], s[40:41], 0, v[16:17]
	s_mov_b32 m0, s42
	s_nop 0
	global_load_lds_dwordx4 v[142:143], off
	v_lshl_add_u64 v[142:143], s[40:41], 0, v[134:135]
	s_add_i32 m0, s42, 0x2000
	s_nop 0
	global_load_lds_dwordx4 v[142:143], off
	s_waitcnt vmcnt(6)
	s_barrier
	s_setprio 1
	v_mfma_f32_16x16x32_bf16 v[50:53], v[212:215], v[170:173], v[50:53]
	v_mfma_f32_16x16x32_bf16 v[42:45], v[220:223], v[170:173], v[42:45]
	v_mfma_f32_16x16x32_bf16 v[34:37], v[212:215], v[188:191], v[34:37]
	v_mfma_f32_16x16x32_bf16 v[26:29], v[220:223], v[188:191], v[26:29]
	v_mfma_f32_16x16x32_bf16 v[18:21], v[212:215], v[196:199], v[18:21]
	v_mfma_f32_16x16x32_bf16 v[8:11], v[220:223], v[196:199], v[8:11]
	v_mfma_f32_16x16x32_bf16 v[4:7], v[212:215], v[204:207], v[4:7]
	v_mfma_f32_16x16x32_bf16 v[0:3], v[220:223], v[204:207], v[0:3]
	v_mfma_f32_16x16x32_bf16 v[50:53], v[216:219], v[174:177], v[50:53]
	v_mfma_f32_16x16x32_bf16 v[42:45], v[224:227], v[174:177], v[42:45]
	v_mfma_f32_16x16x32_bf16 v[34:37], v[216:219], v[192:195], v[34:37]
	v_mfma_f32_16x16x32_bf16 v[26:29], v[224:227], v[192:195], v[26:29]
	v_mfma_f32_16x16x32_bf16 v[18:21], v[216:219], v[200:203], v[18:21]
	v_mfma_f32_16x16x32_bf16 v[8:11], v[224:227], v[200:203], v[8:11]
	v_mfma_f32_16x16x32_bf16 v[4:7], v[216:219], v[208:211], v[4:7]
	v_mfma_f32_16x16x32_bf16 v[0:3], v[224:227], v[208:211], v[0:3]
	s_setprio 0
	s_add_i32 s53, s53, 2
	s_add_u32 s38, s38, 0x100
	s_addc_u32 s39, s39, 0
	s_add_u32 s45, s45, 0x100
	s_addc_u32 s52, s52, 0
	s_cmp_gt_u32 s53, 13
	s_barrier
	s_cbranch_scc0 .LBB0_670
	v_lshl_add_u32 v168, s34, 8, v141
	v_readlane_b32 s38, v252, 38
	v_ashrrev_i32_e32 v169, 31, v168
	v_or_b32_e32 v164, 16, v168
	v_or_b32_e32 v160, 32, v168
	v_or_b32_e32 v154, 48, v168
	v_readlane_b32 s39, v252, 39
	v_ashrrev_i32_e32 v165, 31, v164
	v_ashrrev_i32_e32 v161, 31, v160
	v_ashrrev_i32_e32 v155, 31, v154
	v_lshl_add_u64 v[142:143], v[168:169], 2, s[38:39]
	v_lshl_add_u64 v[146:147], v[164:165], 2, s[38:39]
	v_lshl_add_u64 v[150:151], v[160:161], 2, s[38:39]
	v_lshl_add_u64 v[156:157], v[154:155], 2, s[38:39]
	s_waitcnt vmcnt(6)
	v_mov_b32_e32 v170, v144
	v_mov_b32_e32 v166, v148
	v_mov_b32_e32 v162, v152
	v_mov_b32_e32 v158, v183
	v_mov_b32_e32 v152, v230
	v_mov_b32_e32 v148, v231
	v_mov_b32_e32 v144, v233
	v_mov_b32_e32 v140, v250
	v_add_u32_e32 v156, 0x80, v168
	v_add_u32_e32 v150, 0x90, v168
	v_add_u32_e32 v146, 0xa0, v168
	v_add_u32_e32 v142, 0xb0, v168
	v_lshl_or_b32 v172, s22, 8, v149
	s_cmp_eq_u32 s51, 0
	v_ashrrev_i32_e32 v157, 31, v156
	v_ashrrev_i32_e32 v151, 31, v150
	v_ashrrev_i32_e32 v147, 31, v146
	v_ashrrev_i32_e32 v143, 31, v142
	v_ashrrev_i32_e32 v173, 31, v172
	s_cbranch_scc1 .LBB0_673
	v_mul_f32_e32 v170, 0xbfb8aa3b, v170
	v_mul_f32_e32 v166, 0xbfb8aa3b, v166
	v_mul_f32_e32 v162, 0xbfb8aa3b, v162
	v_mul_f32_e32 v158, 0xbfb8aa3b, v158
	v_mul_f32_e32 v152, 0xbfb8aa3b, v152
	v_mul_f32_e32 v148, 0xbfb8aa3b, v148
	v_mul_f32_e32 v144, 0xbfb8aa3b, v144
	v_mul_f32_e32 v140, 0xbfb8aa3b, v140
	v_mul_f32_e32 v176, v124, v170
	v_exp_f32_e32 v176, v176
	v_mul_f32_e32 v159, v126, v170
	v_mul_f32_e32 v167, v127, v170
	v_lshlrev_b64 v[174:175], 12, v[168:169]
	v_mul_f32_e32 v163, v122, v170
	v_mul_f32_e32 v169, v123, v170
	v_mul_f32_e32 v171, v128, v170
	v_add_f32_e32 v176, 1.0, v176
	v_mul_f32_e32 v177, v129, v170
	v_exp_f32_e32 v159, v159
	v_exp_f32_e32 v167, v167
	v_rcp_f32_e32 v176, v176
	v_mul_f32_e32 v178, v125, v170
	v_exp_f32_e32 v163, v163
	v_exp_f32_e32 v169, v169
	v_exp_f32_e32 v171, v171
	v_exp_f32_e32 v177, v177
	v_exp_f32_e32 v178, v178
	v_add_f32_e32 v159, 1.0, v159
	v_add_f32_e32 v167, 1.0, v167
	v_fma_f32 v176, v176, s31, 0.5
	v_rcp_f32_e32 v159, v159
	v_add_f32_e32 v163, 1.0, v163
	v_rcp_f32_e32 v167, v167
	v_add_f32_e32 v169, 1.0, v169
	v_add_f32_e32 v171, 1.0, v171
	v_max_f32_e32 v176, 1.0, v176
	v_add_f32_e32 v177, 1.0, v177
	v_rcp_f32_e32 v163, v163
	v_rcp_f32_e32 v169, v169
	v_rcp_f32_e32 v171, v171
	v_rcp_f32_e32 v177, v177
	v_cvt_u32_f32_sdwa v179, v176 dst_sel:WORD_1 dst_unused:UNUSED_PAD src0_sel:DWORD
	v_add_f32_e32 v176, 1.0, v178
	v_rcp_f32_e32 v176, v176
	v_fma_f32 v159, v159, s31, 0.5
	v_fma_f32 v167, v167, s31, 0.5
	v_max_f32_e32 v159, 1.0, v159
	v_fma_f32 v163, v163, s31, 0.5
	v_max_f32_e32 v167, 1.0, v167
	v_fma_f32 v169, v169, s31, 0.5
	v_fma_f32 v171, v171, s31, 0.5
	v_fma_f32 v177, v177, s31, 0.5
	v_cvt_u32_f32_e32 v159, v159
	v_max_f32_e32 v163, 1.0, v163
	v_cvt_u32_f32_e32 v167, v167
	v_max_f32_e32 v169, 1.0, v169
	v_max_f32_e32 v171, 1.0, v171
	v_max_f32_e32 v177, 1.0, v177
	v_fma_f32 v176, v176, s31, 0.5
	v_cvt_u32_f32_e32 v163, v163
	v_cvt_u32_f32_e32 v169, v169
	v_cvt_u32_f32_sdwa v171, v171 dst_sel:WORD_1 dst_unused:UNUSED_PAD src0_sel:DWORD
	v_cvt_u32_f32_sdwa v177, v177 dst_sel:BYTE_3 dst_unused:UNUSED_PAD src0_sel:DWORD
	v_max_f32_e32 v176, 1.0, v176
	v_cvt_u32_f32_sdwa v178, v176 dst_sel:BYTE_3 dst_unused:UNUSED_PAD src0_sel:DWORD
	v_readlane_b32 s22, v252, 34
	v_readlane_b32 s23, v252, 35
	v_lshl_or_b32 v159, v167, 8, v159
	v_or3_b32 v176, v159, v171, v177
	v_lshl_add_u64 v[174:175], s[22:23], 0, v[174:175]
	v_lshl_or_b32 v159, v169, 8, v163
	v_lshl_add_u64 v[174:175], v[174:175], 0, v[172:173]
	v_or3_b32 v177, v159, v179, v178
	global_store_dwordx2 v[174:175], v[176:177], off
	v_mul_f32_e32 v176, v108, v170
	v_exp_f32_e32 v176, v176
	v_mul_f32_e32 v159, v114, v170
	v_mul_f32_e32 v167, v115, v170
	v_mul_f32_e32 v163, v106, v170
	v_mul_f32_e32 v169, v107, v170
	v_mul_f32_e32 v171, v116, v170
	v_add_f32_e32 v176, 1.0, v176
	v_mul_f32_e32 v177, v117, v170
	v_exp_f32_e32 v159, v159
	v_exp_f32_e32 v167, v167
	v_rcp_f32_e32 v176, v176
	v_mul_f32_e32 v178, v109, v170
	v_exp_f32_e32 v163, v163
	v_exp_f32_e32 v169, v169
	v_exp_f32_e32 v171, v171
	v_exp_f32_e32 v177, v177
	v_exp_f32_e32 v178, v178
	v_add_f32_e32 v159, 1.0, v159
	v_add_f32_e32 v167, 1.0, v167
	v_fma_f32 v176, v176, s31, 0.5
	v_rcp_f32_e32 v159, v159
	v_add_f32_e32 v163, 1.0, v163
	v_rcp_f32_e32 v167, v167
	v_add_f32_e32 v169, 1.0, v169
	v_add_f32_e32 v171, 1.0, v171
	v_max_f32_e32 v176, 1.0, v176
	v_add_f32_e32 v177, 1.0, v177
	v_rcp_f32_e32 v163, v163
	v_rcp_f32_e32 v169, v169
	v_rcp_f32_e32 v171, v171
	v_rcp_f32_e32 v177, v177
	v_cvt_u32_f32_sdwa v179, v176 dst_sel:WORD_1 dst_unused:UNUSED_PAD src0_sel:DWORD
	v_add_f32_e32 v176, 1.0, v178
	v_rcp_f32_e32 v176, v176
	v_fma_f32 v159, v159, s31, 0.5
	v_fma_f32 v167, v167, s31, 0.5
	v_max_f32_e32 v159, 1.0, v159
	v_fma_f32 v163, v163, s31, 0.5
	v_max_f32_e32 v167, 1.0, v167
	v_fma_f32 v169, v169, s31, 0.5
	v_fma_f32 v171, v171, s31, 0.5
	v_fma_f32 v177, v177, s31, 0.5
	v_cvt_u32_f32_e32 v159, v159
	v_max_f32_e32 v163, 1.0, v163
	v_cvt_u32_f32_e32 v167, v167
	v_max_f32_e32 v169, 1.0, v169
	v_max_f32_e32 v171, 1.0, v171
	v_max_f32_e32 v177, 1.0, v177
	v_fma_f32 v176, v176, s31, 0.5
	v_cvt_u32_f32_e32 v163, v163
	v_cvt_u32_f32_e32 v169, v169
	v_cvt_u32_f32_sdwa v171, v171 dst_sel:WORD_1 dst_unused:UNUSED_PAD src0_sel:DWORD
	v_cvt_u32_f32_sdwa v177, v177 dst_sel:BYTE_3 dst_unused:UNUSED_PAD src0_sel:DWORD
	v_max_f32_e32 v176, 1.0, v176
	v_cvt_u32_f32_sdwa v178, v176 dst_sel:BYTE_3 dst_unused:UNUSED_PAD src0_sel:DWORD
	v_lshl_or_b32 v159, v167, 8, v159
	v_or3_b32 v176, v159, v171, v177
	v_lshl_or_b32 v159, v169, 8, v163
	v_or3_b32 v177, v159, v179, v178
	global_store_dwordx2 v[174:175], v[176:177], off offset:128
	v_lshlrev_b64 v[174:175], 12, v[164:165]
	v_mul_f32_e32 v159, v118, v166
	v_mul_f32_e32 v165, v119, v166
	v_mul_f32_e32 v163, v110, v166
	v_mul_f32_e32 v167, v111, v166
	v_mul_f32_e32 v169, v120, v166
	v_mul_f32_e32 v176, v121, v166
	v_exp_f32_e32 v159, v159
	v_exp_f32_e32 v165, v165
	v_mul_f32_e32 v171, v112, v166
	v_mul_f32_e32 v177, v113, v166
	v_exp_f32_e32 v163, v163
	v_exp_f32_e32 v167, v167
	v_exp_f32_e32 v169, v169
	v_exp_f32_e32 v176, v176
	v_exp_f32_e32 v171, v171
	v_exp_f32_e32 v177, v177
	v_add_f32_e32 v159, 1.0, v159
	v_add_f32_e32 v165, 1.0, v165
	v_rcp_f32_e32 v159, v159
	v_add_f32_e32 v163, 1.0, v163
	v_rcp_f32_e32 v165, v165
	v_add_f32_e32 v167, 1.0, v167
	v_add_f32_e32 v169, 1.0, v169
	v_add_f32_e32 v176, 1.0, v176
	v_rcp_f32_e32 v163, v163
	v_rcp_f32_e32 v167, v167
	v_rcp_f32_e32 v169, v169
	v_add_f32_e32 v171, 1.0, v171
	v_rcp_f32_e32 v176, v176
	v_add_f32_e32 v177, 1.0, v177
	v_rcp_f32_e32 v171, v171
	v_rcp_f32_e32 v177, v177
	v_fma_f32 v159, v159, s31, 0.5
	v_fma_f32 v165, v165, s31, 0.5
	v_max_f32_e32 v159, 1.0, v159
	v_fma_f32 v163, v163, s31, 0.5
	v_max_f32_e32 v165, 1.0, v165
	v_fma_f32 v167, v167, s31, 0.5
	v_fma_f32 v169, v169, s31, 0.5
	v_fma_f32 v176, v176, s31, 0.5
	v_cvt_u32_f32_e32 v159, v159
	v_max_f32_e32 v163, 1.0, v163
	v_cvt_u32_f32_e32 v165, v165
	v_max_f32_e32 v167, 1.0, v167
	v_max_f32_e32 v169, 1.0, v169
	v_fma_f32 v171, v171, s31, 0.5
	v_max_f32_e32 v176, 1.0, v176
	v_fma_f32 v177, v177, s31, 0.5
	v_cvt_u32_f32_e32 v163, v163
	v_cvt_u32_f32_e32 v167, v167
	v_cvt_u32_f32_sdwa v169, v169 dst_sel:WORD_1 dst_unused:UNUSED_PAD src0_sel:DWORD
	v_max_f32_e32 v171, 1.0, v171
	v_cvt_u32_f32_sdwa v176, v176 dst_sel:BYTE_3 dst_unused:UNUSED_PAD src0_sel:DWORD
	v_max_f32_e32 v177, 1.0, v177
	v_cvt_u32_f32_sdwa v171, v171 dst_sel:WORD_1 dst_unused:UNUSED_PAD src0_sel:DWORD
	v_cvt_u32_f32_sdwa v177, v177 dst_sel:BYTE_3 dst_unused:UNUSED_PAD src0_sel:DWORD
	v_lshl_or_b32 v159, v165, 8, v159
	v_lshl_add_u64 v[174:175], s[22:23], 0, v[174:175]
	v_or3_b32 v176, v159, v169, v176
	v_lshl_or_b32 v159, v167, 8, v163
	v_lshl_add_u64 v[174:175], v[174:175], 0, v[172:173]
	v_or3_b32 v177, v159, v171, v177
	v_mul_f32_e32 v159, v98, v166
	v_mul_f32_e32 v165, v99, v166
	v_mul_f32_e32 v163, v90, v166
	global_store_dwordx2 v[174:175], v[176:177], off
	v_mul_f32_e32 v167, v91, v166
	v_mul_f32_e32 v169, v100, v166
	v_mul_f32_e32 v176, v101, v166
	v_exp_f32_e32 v159, v159
	v_exp_f32_e32 v165, v165
	v_mul_f32_e32 v171, v92, v166
	v_mul_f32_e32 v177, v93, v166
	v_exp_f32_e32 v163, v163
	v_exp_f32_e32 v167, v167
	v_exp_f32_e32 v169, v169
	v_exp_f32_e32 v176, v176
	v_exp_f32_e32 v171, v171
	v_exp_f32_e32 v177, v177
	v_add_f32_e32 v159, 1.0, v159
	v_add_f32_e32 v165, 1.0, v165
	v_rcp_f32_e32 v159, v159
	v_add_f32_e32 v163, 1.0, v163
	v_rcp_f32_e32 v165, v165
	v_add_f32_e32 v167, 1.0, v167
	v_add_f32_e32 v169, 1.0, v169
	v_add_f32_e32 v176, 1.0, v176
	v_rcp_f32_e32 v163, v163
	v_rcp_f32_e32 v167, v167
	v_rcp_f32_e32 v169, v169
	v_add_f32_e32 v171, 1.0, v171
	v_rcp_f32_e32 v176, v176
	v_add_f32_e32 v177, 1.0, v177
	v_rcp_f32_e32 v171, v171
	v_rcp_f32_e32 v177, v177
	v_fma_f32 v159, v159, s31, 0.5
	v_fma_f32 v165, v165, s31, 0.5
	v_max_f32_e32 v159, 1.0, v159
	v_fma_f32 v163, v163, s31, 0.5
	v_max_f32_e32 v165, 1.0, v165
	v_fma_f32 v167, v167, s31, 0.5
	v_fma_f32 v169, v169, s31, 0.5
	v_fma_f32 v176, v176, s31, 0.5
	v_cvt_u32_f32_e32 v159, v159
	v_max_f32_e32 v163, 1.0, v163
	v_cvt_u32_f32_e32 v165, v165
	v_max_f32_e32 v167, 1.0, v167
	v_max_f32_e32 v169, 1.0, v169
	v_fma_f32 v171, v171, s31, 0.5
	v_max_f32_e32 v176, 1.0, v176
	v_fma_f32 v177, v177, s31, 0.5
	v_cvt_u32_f32_e32 v163, v163
	v_cvt_u32_f32_e32 v167, v167
	v_cvt_u32_f32_sdwa v169, v169 dst_sel:WORD_1 dst_unused:UNUSED_PAD src0_sel:DWORD
	v_max_f32_e32 v171, 1.0, v171
	v_cvt_u32_f32_sdwa v176, v176 dst_sel:BYTE_3 dst_unused:UNUSED_PAD src0_sel:DWORD
	v_max_f32_e32 v177, 1.0, v177
	v_cvt_u32_f32_sdwa v171, v171 dst_sel:WORD_1 dst_unused:UNUSED_PAD src0_sel:DWORD
	v_cvt_u32_f32_sdwa v177, v177 dst_sel:BYTE_3 dst_unused:UNUSED_PAD src0_sel:DWORD
	v_lshl_or_b32 v159, v165, 8, v159
	v_or3_b32 v176, v159, v169, v176
	v_lshl_or_b32 v159, v167, 8, v163
	v_or3_b32 v177, v159, v171, v177
	v_mul_f32_e32 v159, v102, v162
	v_mul_f32_e32 v163, v103, v162
	global_store_dwordx2 v[174:175], v[176:177], off offset:128
	v_lshlrev_b64 v[174:175], 12, v[160:161]
	v_mul_f32_e32 v161, v94, v162
	v_mul_f32_e32 v165, v95, v162
	v_mul_f32_e32 v167, v104, v162
	v_mul_f32_e32 v171, v105, v162
	v_exp_f32_e32 v159, v159
	v_exp_f32_e32 v163, v163
	v_mul_f32_e32 v169, v96, v162
	v_mul_f32_e32 v176, v97, v162
	v_exp_f32_e32 v161, v161
	v_exp_f32_e32 v165, v165
	v_exp_f32_e32 v167, v167
	v_exp_f32_e32 v171, v171
	v_exp_f32_e32 v169, v169
	v_exp_f32_e32 v176, v176
	v_add_f32_e32 v159, 1.0, v159
	v_add_f32_e32 v163, 1.0, v163
	v_rcp_f32_e32 v159, v159
	v_add_f32_e32 v161, 1.0, v161
	v_rcp_f32_e32 v163, v163
	v_add_f32_e32 v165, 1.0, v165
	v_add_f32_e32 v167, 1.0, v167
	v_add_f32_e32 v171, 1.0, v171
	v_rcp_f32_e32 v161, v161
	v_rcp_f32_e32 v165, v165
	v_rcp_f32_e32 v167, v167
	v_add_f32_e32 v169, 1.0, v169
	v_rcp_f32_e32 v171, v171
	v_add_f32_e32 v176, 1.0, v176
	v_rcp_f32_e32 v169, v169
	v_rcp_f32_e32 v176, v176
	v_fma_f32 v159, v159, s31, 0.5
	v_fma_f32 v163, v163, s31, 0.5
	v_max_f32_e32 v159, 1.0, v159
	v_fma_f32 v161, v161, s31, 0.5
	v_max_f32_e32 v163, 1.0, v163
	v_fma_f32 v165, v165, s31, 0.5
	v_fma_f32 v167, v167, s31, 0.5
	v_fma_f32 v171, v171, s31, 0.5
	v_cvt_u32_f32_e32 v159, v159
	v_max_f32_e32 v161, 1.0, v161
	v_cvt_u32_f32_e32 v163, v163
	v_max_f32_e32 v165, 1.0, v165
	v_max_f32_e32 v167, 1.0, v167
	v_fma_f32 v169, v169, s31, 0.5
	v_max_f32_e32 v171, 1.0, v171
	v_fma_f32 v176, v176, s31, 0.5
	v_cvt_u32_f32_e32 v161, v161
	v_cvt_u32_f32_e32 v165, v165
	v_cvt_u32_f32_sdwa v167, v167 dst_sel:WORD_1 dst_unused:UNUSED_PAD src0_sel:DWORD
	v_max_f32_e32 v169, 1.0, v169
	v_cvt_u32_f32_sdwa v171, v171 dst_sel:BYTE_3 dst_unused:UNUSED_PAD src0_sel:DWORD
	v_max_f32_e32 v176, 1.0, v176
	v_cvt_u32_f32_sdwa v169, v169 dst_sel:WORD_1 dst_unused:UNUSED_PAD src0_sel:DWORD
	v_cvt_u32_f32_sdwa v177, v176 dst_sel:BYTE_3 dst_unused:UNUSED_PAD src0_sel:DWORD
	v_lshl_or_b32 v159, v163, 8, v159
	v_or3_b32 v176, v159, v167, v171
	v_lshl_or_b32 v159, v165, 8, v161
	v_lshl_add_u64 v[174:175], s[22:23], 0, v[174:175]
	v_or3_b32 v177, v159, v169, v177
	v_mul_f32_e32 v159, v82, v162
	v_mul_f32_e32 v163, v83, v162
	v_lshl_add_u64 v[174:175], v[174:175], 0, v[172:173]
	v_mul_f32_e32 v161, v74, v162
	v_mul_f32_e32 v165, v75, v162
	v_mul_f32_e32 v167, v84, v162
	v_mul_f32_e32 v171, v85, v162
	v_exp_f32_e32 v159, v159
	global_store_dwordx2 v[174:175], v[176:177], off
	v_exp_f32_e32 v163, v163
	v_mul_f32_e32 v169, v76, v162
	v_mul_f32_e32 v176, v77, v162
	v_exp_f32_e32 v161, v161
	v_exp_f32_e32 v165, v165
	v_exp_f32_e32 v167, v167
	v_exp_f32_e32 v171, v171
	v_exp_f32_e32 v169, v169
	v_exp_f32_e32 v176, v176
	v_add_f32_e32 v159, 1.0, v159
	v_add_f32_e32 v163, 1.0, v163
	v_rcp_f32_e32 v159, v159
	v_add_f32_e32 v161, 1.0, v161
	v_rcp_f32_e32 v163, v163
	v_add_f32_e32 v165, 1.0, v165
	v_add_f32_e32 v167, 1.0, v167
	v_add_f32_e32 v171, 1.0, v171
	v_rcp_f32_e32 v161, v161
	v_rcp_f32_e32 v165, v165
	v_rcp_f32_e32 v167, v167
	v_add_f32_e32 v169, 1.0, v169
	v_rcp_f32_e32 v171, v171
	v_add_f32_e32 v176, 1.0, v176
	v_rcp_f32_e32 v169, v169
	v_rcp_f32_e32 v176, v176
	v_fma_f32 v159, v159, s31, 0.5
	v_fma_f32 v163, v163, s31, 0.5
	v_max_f32_e32 v159, 1.0, v159
	v_fma_f32 v161, v161, s31, 0.5
	v_max_f32_e32 v163, 1.0, v163
	v_fma_f32 v165, v165, s31, 0.5
	v_fma_f32 v167, v167, s31, 0.5
	v_fma_f32 v171, v171, s31, 0.5
	v_cvt_u32_f32_e32 v159, v159
	v_max_f32_e32 v161, 1.0, v161
	v_cvt_u32_f32_e32 v163, v163
	v_max_f32_e32 v165, 1.0, v165
	v_max_f32_e32 v167, 1.0, v167
	v_fma_f32 v169, v169, s31, 0.5
	v_max_f32_e32 v171, 1.0, v171
	v_fma_f32 v176, v176, s31, 0.5
	v_cvt_u32_f32_e32 v161, v161
	v_cvt_u32_f32_e32 v165, v165
	v_cvt_u32_f32_sdwa v167, v167 dst_sel:WORD_1 dst_unused:UNUSED_PAD src0_sel:DWORD
	v_max_f32_e32 v169, 1.0, v169
	v_cvt_u32_f32_sdwa v171, v171 dst_sel:BYTE_3 dst_unused:UNUSED_PAD src0_sel:DWORD
	v_max_f32_e32 v176, 1.0, v176
	v_cvt_u32_f32_sdwa v169, v169 dst_sel:WORD_1 dst_unused:UNUSED_PAD src0_sel:DWORD
	v_cvt_u32_f32_sdwa v177, v176 dst_sel:BYTE_3 dst_unused:UNUSED_PAD src0_sel:DWORD
	v_lshl_or_b32 v159, v163, 8, v159
	v_or3_b32 v176, v159, v167, v171
	v_lshl_or_b32 v159, v165, 8, v161
	v_or3_b32 v177, v159, v169, v177
	global_store_dwordx2 v[174:175], v[176:177], off offset:128
	v_lshlrev_b64 v[174:175], 12, v[154:155]
	v_mul_f32_e32 v155, v86, v158
	v_mul_f32_e32 v161, v87, v158
	v_mul_f32_e32 v159, v78, v158
	v_mul_f32_e32 v163, v79, v158
	v_mul_f32_e32 v165, v88, v158
	v_mul_f32_e32 v169, v89, v158
	v_exp_f32_e32 v155, v155
	v_exp_f32_e32 v161, v161
	v_mul_f32_e32 v167, v80, v158
	v_mul_f32_e32 v171, v81, v158
	v_exp_f32_e32 v159, v159
	v_exp_f32_e32 v163, v163
	v_exp_f32_e32 v165, v165
	v_exp_f32_e32 v169, v169
	v_exp_f32_e32 v167, v167
	v_exp_f32_e32 v171, v171
	v_add_f32_e32 v155, 1.0, v155
	v_add_f32_e32 v161, 1.0, v161
	v_rcp_f32_e32 v155, v155
	v_add_f32_e32 v159, 1.0, v159
	v_rcp_f32_e32 v161, v161
	v_add_f32_e32 v163, 1.0, v163
	v_add_f32_e32 v165, 1.0, v165
	v_add_f32_e32 v169, 1.0, v169
	v_rcp_f32_e32 v159, v159
	v_rcp_f32_e32 v163, v163
	v_rcp_f32_e32 v165, v165
	v_add_f32_e32 v167, 1.0, v167
	v_rcp_f32_e32 v169, v169
	v_add_f32_e32 v171, 1.0, v171
	v_rcp_f32_e32 v167, v167
	v_rcp_f32_e32 v171, v171
	v_fma_f32 v155, v155, s31, 0.5
	v_fma_f32 v161, v161, s31, 0.5
	v_max_f32_e32 v155, 1.0, v155
	v_fma_f32 v159, v159, s31, 0.5
	v_max_f32_e32 v161, 1.0, v161
	v_fma_f32 v163, v163, s31, 0.5
	v_fma_f32 v165, v165, s31, 0.5
	v_fma_f32 v169, v169, s31, 0.5
	v_cvt_u32_f32_e32 v155, v155
	v_max_f32_e32 v159, 1.0, v159
	v_cvt_u32_f32_e32 v161, v161
	v_max_f32_e32 v163, 1.0, v163
	v_max_f32_e32 v165, 1.0, v165
	v_fma_f32 v167, v167, s31, 0.5
	v_max_f32_e32 v169, 1.0, v169
	v_fma_f32 v171, v171, s31, 0.5
	v_cvt_u32_f32_e32 v159, v159
	v_cvt_u32_f32_e32 v163, v163
	v_cvt_u32_f32_sdwa v165, v165 dst_sel:WORD_1 dst_unused:UNUSED_PAD src0_sel:DWORD
	v_max_f32_e32 v167, 1.0, v167
	v_cvt_u32_f32_sdwa v169, v169 dst_sel:BYTE_3 dst_unused:UNUSED_PAD src0_sel:DWORD
	v_max_f32_e32 v171, 1.0, v171
	v_cvt_u32_f32_sdwa v167, v167 dst_sel:WORD_1 dst_unused:UNUSED_PAD src0_sel:DWORD
	v_cvt_u32_f32_sdwa v171, v171 dst_sel:BYTE_3 dst_unused:UNUSED_PAD src0_sel:DWORD
	v_lshl_or_b32 v155, v161, 8, v155
	v_or3_b32 v176, v155, v165, v169
	v_lshl_or_b32 v155, v163, 8, v159
	v_or3_b32 v177, v155, v167, v171
	v_mul_f32_e32 v155, v70, v158
	v_mul_f32_e32 v161, v71, v158
	v_mul_f32_e32 v159, v66, v158
	v_mul_f32_e32 v163, v67, v158
	v_mul_f32_e32 v165, v72, v158
	v_mul_f32_e32 v169, v73, v158
	v_exp_f32_e32 v155, v155
	v_exp_f32_e32 v161, v161
	v_mul_f32_e32 v167, v68, v158
	v_mul_f32_e32 v171, v69, v158
	v_exp_f32_e32 v159, v159
	v_exp_f32_e32 v163, v163
	v_exp_f32_e32 v165, v165
	v_exp_f32_e32 v169, v169
	v_exp_f32_e32 v167, v167
	v_exp_f32_e32 v171, v171
	v_add_f32_e32 v155, 1.0, v155
	v_add_f32_e32 v161, 1.0, v161
	v_rcp_f32_e32 v155, v155
	v_add_f32_e32 v159, 1.0, v159
	v_rcp_f32_e32 v161, v161
	v_add_f32_e32 v163, 1.0, v163
	v_add_f32_e32 v165, 1.0, v165
	v_add_f32_e32 v169, 1.0, v169
	v_rcp_f32_e32 v159, v159
	v_rcp_f32_e32 v163, v163
	v_rcp_f32_e32 v165, v165
	v_add_f32_e32 v167, 1.0, v167
	v_rcp_f32_e32 v169, v169
	v_add_f32_e32 v171, 1.0, v171
	v_rcp_f32_e32 v167, v167
	v_rcp_f32_e32 v171, v171
	v_fma_f32 v155, v155, s31, 0.5
	v_fma_f32 v161, v161, s31, 0.5
	v_max_f32_e32 v155, 1.0, v155
	v_fma_f32 v159, v159, s31, 0.5
	v_max_f32_e32 v161, 1.0, v161
	v_fma_f32 v163, v163, s31, 0.5
	v_fma_f32 v165, v165, s31, 0.5
	v_fma_f32 v169, v169, s31, 0.5
	v_cvt_u32_f32_e32 v155, v155
	v_max_f32_e32 v159, 1.0, v159
	v_cvt_u32_f32_e32 v161, v161
	v_max_f32_e32 v163, 1.0, v163
	v_max_f32_e32 v165, 1.0, v165
	v_fma_f32 v167, v167, s31, 0.5
	v_max_f32_e32 v169, 1.0, v169
	v_fma_f32 v171, v171, s31, 0.5
	v_cvt_u32_f32_e32 v159, v159
	v_cvt_u32_f32_e32 v163, v163
	v_cvt_u32_f32_sdwa v165, v165 dst_sel:WORD_1 dst_unused:UNUSED_PAD src0_sel:DWORD
	v_max_f32_e32 v167, 1.0, v167
	v_cvt_u32_f32_sdwa v169, v169 dst_sel:BYTE_3 dst_unused:UNUSED_PAD src0_sel:DWORD
	v_max_f32_e32 v171, 1.0, v171
	v_cvt_u32_f32_sdwa v167, v167 dst_sel:WORD_1 dst_unused:UNUSED_PAD src0_sel:DWORD
	v_cvt_u32_f32_sdwa v171, v171 dst_sel:BYTE_3 dst_unused:UNUSED_PAD src0_sel:DWORD
	v_lshl_add_u64 v[174:175], s[22:23], 0, v[174:175]
	v_lshl_add_u64 v[174:175], v[174:175], 0, v[172:173]
	v_lshl_or_b32 v155, v161, 8, v155
	global_store_dwordx2 v[174:175], v[176:177], off
	v_or3_b32 v176, v155, v165, v169
	v_lshl_or_b32 v155, v163, 8, v159
	v_or3_b32 v177, v155, v167, v171
	v_mul_f32_e32 v155, v62, v152
	v_mul_f32_e32 v159, v63, v152
	global_store_dwordx2 v[174:175], v[176:177], off offset:128
	v_lshlrev_b64 v[174:175], 12, v[156:157]
	v_mul_f32_e32 v157, v58, v152
	v_mul_f32_e32 v161, v59, v152
	v_mul_f32_e32 v163, v64, v152
	v_mul_f32_e32 v167, v65, v152
	v_exp_f32_e32 v155, v155
	v_exp_f32_e32 v159, v159
	v_mul_f32_e32 v165, v60, v152
	v_mul_f32_e32 v169, v61, v152
	v_exp_f32_e32 v157, v157
	v_exp_f32_e32 v161, v161
	v_exp_f32_e32 v163, v163
	v_exp_f32_e32 v167, v167
	v_exp_f32_e32 v165, v165
	v_exp_f32_e32 v169, v169
	v_add_f32_e32 v155, 1.0, v155
	v_add_f32_e32 v159, 1.0, v159
	v_rcp_f32_e32 v155, v155
	v_add_f32_e32 v157, 1.0, v157
	v_rcp_f32_e32 v159, v159
	v_add_f32_e32 v161, 1.0, v161
	v_add_f32_e32 v163, 1.0, v163
	v_add_f32_e32 v167, 1.0, v167
	v_rcp_f32_e32 v157, v157
	v_rcp_f32_e32 v161, v161
	v_rcp_f32_e32 v163, v163
	v_add_f32_e32 v165, 1.0, v165
	v_rcp_f32_e32 v167, v167
	v_add_f32_e32 v169, 1.0, v169
	v_rcp_f32_e32 v165, v165
	v_rcp_f32_e32 v169, v169
	v_fma_f32 v155, v155, s31, 0.5
	v_fma_f32 v159, v159, s31, 0.5
	v_max_f32_e32 v155, 1.0, v155
	v_fma_f32 v157, v157, s31, 0.5
	v_max_f32_e32 v159, 1.0, v159
	v_fma_f32 v161, v161, s31, 0.5
	v_fma_f32 v163, v163, s31, 0.5
	v_fma_f32 v167, v167, s31, 0.5
	v_cvt_u32_f32_e32 v155, v155
	v_max_f32_e32 v157, 1.0, v157
	v_cvt_u32_f32_e32 v159, v159
	v_max_f32_e32 v161, 1.0, v161
	v_max_f32_e32 v163, 1.0, v163
	v_fma_f32 v165, v165, s31, 0.5
	v_max_f32_e32 v167, 1.0, v167
	v_fma_f32 v169, v169, s31, 0.5
	v_cvt_u32_f32_e32 v157, v157
	v_cvt_u32_f32_e32 v161, v161
	v_cvt_u32_f32_sdwa v163, v163 dst_sel:WORD_1 dst_unused:UNUSED_PAD src0_sel:DWORD
	v_max_f32_e32 v165, 1.0, v165
	v_cvt_u32_f32_sdwa v167, v167 dst_sel:BYTE_3 dst_unused:UNUSED_PAD src0_sel:DWORD
	v_max_f32_e32 v169, 1.0, v169
	v_cvt_u32_f32_sdwa v165, v165 dst_sel:WORD_1 dst_unused:UNUSED_PAD src0_sel:DWORD
	v_cvt_u32_f32_sdwa v169, v169 dst_sel:BYTE_3 dst_unused:UNUSED_PAD src0_sel:DWORD
	v_lshl_or_b32 v155, v159, 8, v155
	v_or3_b32 v176, v155, v163, v167
	v_lshl_or_b32 v155, v161, 8, v157
	v_or3_b32 v177, v155, v165, v169
	v_mul_f32_e32 v155, v50, v152
	v_mul_f32_e32 v159, v51, v152
	v_mul_f32_e32 v157, v42, v152
	v_mul_f32_e32 v161, v43, v152
	v_mul_f32_e32 v163, v52, v152
	v_mul_f32_e32 v167, v53, v152
	v_exp_f32_e32 v155, v155
	v_exp_f32_e32 v159, v159
	v_mul_f32_e32 v165, v44, v152
	v_mul_f32_e32 v169, v45, v152
	v_exp_f32_e32 v157, v157
	v_exp_f32_e32 v161, v161
	v_exp_f32_e32 v163, v163
	v_exp_f32_e32 v167, v167
	v_exp_f32_e32 v165, v165
	v_exp_f32_e32 v169, v169
	v_add_f32_e32 v155, 1.0, v155
	v_add_f32_e32 v159, 1.0, v159
	v_rcp_f32_e32 v155, v155
	v_add_f32_e32 v157, 1.0, v157
	v_rcp_f32_e32 v159, v159
	v_add_f32_e32 v161, 1.0, v161
	v_add_f32_e32 v163, 1.0, v163
	v_add_f32_e32 v167, 1.0, v167
	v_rcp_f32_e32 v157, v157
	v_rcp_f32_e32 v161, v161
	v_rcp_f32_e32 v163, v163
	v_add_f32_e32 v165, 1.0, v165
	v_rcp_f32_e32 v167, v167
	v_add_f32_e32 v169, 1.0, v169
	v_rcp_f32_e32 v165, v165
	v_rcp_f32_e32 v169, v169
	v_fma_f32 v155, v155, s31, 0.5
	v_fma_f32 v159, v159, s31, 0.5
	v_max_f32_e32 v155, 1.0, v155
	v_fma_f32 v157, v157, s31, 0.5
	v_max_f32_e32 v159, 1.0, v159
	v_fma_f32 v161, v161, s31, 0.5
	v_fma_f32 v163, v163, s31, 0.5
	v_fma_f32 v167, v167, s31, 0.5
	v_cvt_u32_f32_e32 v155, v155
	v_max_f32_e32 v157, 1.0, v157
	v_cvt_u32_f32_e32 v159, v159
	v_max_f32_e32 v161, 1.0, v161
	v_max_f32_e32 v163, 1.0, v163
	v_fma_f32 v165, v165, s31, 0.5
	v_max_f32_e32 v167, 1.0, v167
	v_fma_f32 v169, v169, s31, 0.5
	v_cvt_u32_f32_e32 v157, v157
	v_cvt_u32_f32_e32 v161, v161
	v_cvt_u32_f32_sdwa v163, v163 dst_sel:WORD_1 dst_unused:UNUSED_PAD src0_sel:DWORD
	v_max_f32_e32 v165, 1.0, v165
	v_cvt_u32_f32_sdwa v167, v167 dst_sel:BYTE_3 dst_unused:UNUSED_PAD src0_sel:DWORD
	v_max_f32_e32 v169, 1.0, v169
	v_cvt_u32_f32_sdwa v165, v165 dst_sel:WORD_1 dst_unused:UNUSED_PAD src0_sel:DWORD
	v_cvt_u32_f32_sdwa v169, v169 dst_sel:BYTE_3 dst_unused:UNUSED_PAD src0_sel:DWORD
	v_lshl_add_u64 v[174:175], s[22:23], 0, v[174:175]
	v_lshl_add_u64 v[174:175], v[174:175], 0, v[172:173]
	v_lshl_or_b32 v155, v159, 8, v155
	global_store_dwordx2 v[174:175], v[176:177], off
	v_or3_b32 v176, v155, v163, v167
	v_lshl_or_b32 v155, v161, 8, v157
	v_or3_b32 v177, v155, v165, v169
	global_store_dwordx2 v[174:175], v[176:177], off offset:128
	v_lshlrev_b64 v[174:175], 12, v[150:151]
	v_mul_f32_e32 v151, v54, v148
	v_mul_f32_e32 v157, v55, v148
	v_mul_f32_e32 v155, v46, v148
	v_mul_f32_e32 v159, v47, v148
	v_mul_f32_e32 v161, v56, v148
	v_mul_f32_e32 v165, v57, v148
	v_exp_f32_e32 v151, v151
	v_exp_f32_e32 v157, v157
	v_mul_f32_e32 v163, v48, v148
	v_mul_f32_e32 v167, v49, v148
	v_exp_f32_e32 v155, v155
	v_exp_f32_e32 v159, v159
	v_exp_f32_e32 v161, v161
	v_exp_f32_e32 v165, v165
	v_exp_f32_e32 v163, v163
	v_exp_f32_e32 v167, v167
	v_add_f32_e32 v151, 1.0, v151
	v_add_f32_e32 v157, 1.0, v157
	v_rcp_f32_e32 v151, v151
	v_add_f32_e32 v155, 1.0, v155
	v_rcp_f32_e32 v157, v157
	v_add_f32_e32 v159, 1.0, v159
	v_add_f32_e32 v161, 1.0, v161
	v_add_f32_e32 v165, 1.0, v165
	v_rcp_f32_e32 v155, v155
	v_rcp_f32_e32 v159, v159
	v_rcp_f32_e32 v161, v161
	v_add_f32_e32 v163, 1.0, v163
	v_rcp_f32_e32 v165, v165
	v_add_f32_e32 v167, 1.0, v167
	v_rcp_f32_e32 v163, v163
	v_rcp_f32_e32 v167, v167
	v_fma_f32 v151, v151, s31, 0.5
	v_fma_f32 v157, v157, s31, 0.5
	v_max_f32_e32 v151, 1.0, v151
	v_fma_f32 v155, v155, s31, 0.5
	v_max_f32_e32 v157, 1.0, v157
	v_fma_f32 v159, v159, s31, 0.5
	v_fma_f32 v161, v161, s31, 0.5
	v_fma_f32 v165, v165, s31, 0.5
	v_cvt_u32_f32_e32 v151, v151
	v_max_f32_e32 v155, 1.0, v155
	v_cvt_u32_f32_e32 v157, v157
	v_max_f32_e32 v159, 1.0, v159
	v_max_f32_e32 v161, 1.0, v161
	v_fma_f32 v163, v163, s31, 0.5
	v_max_f32_e32 v165, 1.0, v165
	v_fma_f32 v167, v167, s31, 0.5
	v_cvt_u32_f32_e32 v155, v155
	v_cvt_u32_f32_e32 v159, v159
	v_cvt_u32_f32_sdwa v161, v161 dst_sel:WORD_1 dst_unused:UNUSED_PAD src0_sel:DWORD
	v_max_f32_e32 v163, 1.0, v163
	v_cvt_u32_f32_sdwa v165, v165 dst_sel:BYTE_3 dst_unused:UNUSED_PAD src0_sel:DWORD
	v_max_f32_e32 v167, 1.0, v167
	v_cvt_u32_f32_sdwa v163, v163 dst_sel:WORD_1 dst_unused:UNUSED_PAD src0_sel:DWORD
	v_cvt_u32_f32_sdwa v167, v167 dst_sel:BYTE_3 dst_unused:UNUSED_PAD src0_sel:DWORD
	v_lshl_or_b32 v151, v157, 8, v151
	v_or3_b32 v176, v151, v161, v165
	v_lshl_or_b32 v151, v159, 8, v155
	v_or3_b32 v177, v151, v163, v167
	v_mul_f32_e32 v151, v34, v148
	v_mul_f32_e32 v157, v35, v148
	v_mul_f32_e32 v155, v26, v148
	v_mul_f32_e32 v159, v27, v148
	v_mul_f32_e32 v161, v36, v148
	v_mul_f32_e32 v165, v37, v148
	v_exp_f32_e32 v151, v151
	v_exp_f32_e32 v157, v157
	v_mul_f32_e32 v163, v28, v148
	v_mul_f32_e32 v167, v29, v148
	v_exp_f32_e32 v155, v155
	v_exp_f32_e32 v159, v159
	v_exp_f32_e32 v161, v161
	v_exp_f32_e32 v165, v165
	v_exp_f32_e32 v163, v163
	v_exp_f32_e32 v167, v167
	v_add_f32_e32 v151, 1.0, v151
	v_add_f32_e32 v157, 1.0, v157
	v_rcp_f32_e32 v151, v151
	v_add_f32_e32 v155, 1.0, v155
	v_rcp_f32_e32 v157, v157
	v_add_f32_e32 v159, 1.0, v159
	v_add_f32_e32 v161, 1.0, v161
	v_add_f32_e32 v165, 1.0, v165
	v_rcp_f32_e32 v155, v155
	v_rcp_f32_e32 v159, v159
	v_rcp_f32_e32 v161, v161
	v_add_f32_e32 v163, 1.0, v163
	v_rcp_f32_e32 v165, v165
	v_add_f32_e32 v167, 1.0, v167
	v_rcp_f32_e32 v163, v163
	v_rcp_f32_e32 v167, v167
	v_fma_f32 v151, v151, s31, 0.5
	v_fma_f32 v157, v157, s31, 0.5
	v_max_f32_e32 v151, 1.0, v151
	v_fma_f32 v155, v155, s31, 0.5
	v_max_f32_e32 v157, 1.0, v157
	v_fma_f32 v159, v159, s31, 0.5
	v_fma_f32 v161, v161, s31, 0.5
	v_fma_f32 v165, v165, s31, 0.5
	v_cvt_u32_f32_e32 v151, v151
	v_max_f32_e32 v155, 1.0, v155
	v_cvt_u32_f32_e32 v157, v157
	v_max_f32_e32 v159, 1.0, v159
	v_max_f32_e32 v161, 1.0, v161
	v_fma_f32 v163, v163, s31, 0.5
	v_max_f32_e32 v165, 1.0, v165
	v_fma_f32 v167, v167, s31, 0.5
	v_cvt_u32_f32_e32 v155, v155
	v_cvt_u32_f32_e32 v159, v159
	v_cvt_u32_f32_sdwa v161, v161 dst_sel:WORD_1 dst_unused:UNUSED_PAD src0_sel:DWORD
	v_max_f32_e32 v163, 1.0, v163
	v_cvt_u32_f32_sdwa v165, v165 dst_sel:BYTE_3 dst_unused:UNUSED_PAD src0_sel:DWORD
	v_max_f32_e32 v167, 1.0, v167
	v_cvt_u32_f32_sdwa v163, v163 dst_sel:WORD_1 dst_unused:UNUSED_PAD src0_sel:DWORD
	v_cvt_u32_f32_sdwa v167, v167 dst_sel:BYTE_3 dst_unused:UNUSED_PAD src0_sel:DWORD
	v_lshl_add_u64 v[174:175], s[22:23], 0, v[174:175]
	v_lshl_add_u64 v[174:175], v[174:175], 0, v[172:173]
	v_lshl_or_b32 v151, v157, 8, v151
	global_store_dwordx2 v[174:175], v[176:177], off
	v_or3_b32 v176, v151, v161, v165
	v_lshl_or_b32 v151, v159, 8, v155
	v_or3_b32 v177, v151, v163, v167
	global_store_dwordx2 v[174:175], v[176:177], off offset:128
	v_lshlrev_b64 v[174:175], 12, v[146:147]
	v_mul_f32_e32 v147, v38, v144
	v_mul_f32_e32 v155, v39, v144
	v_mul_f32_e32 v151, v30, v144
	v_mul_f32_e32 v157, v31, v144
	v_mul_f32_e32 v159, v40, v144
	v_mul_f32_e32 v163, v41, v144
	v_exp_f32_e32 v147, v147
	v_exp_f32_e32 v155, v155
	v_mul_f32_e32 v161, v32, v144
	v_mul_f32_e32 v165, v33, v144
	v_exp_f32_e32 v151, v151
	v_exp_f32_e32 v157, v157
	v_exp_f32_e32 v159, v159
	v_exp_f32_e32 v163, v163
	v_exp_f32_e32 v161, v161
	v_exp_f32_e32 v165, v165
	v_add_f32_e32 v147, 1.0, v147
	v_add_f32_e32 v155, 1.0, v155
	v_rcp_f32_e32 v147, v147
	v_add_f32_e32 v151, 1.0, v151
	v_rcp_f32_e32 v155, v155
	v_add_f32_e32 v157, 1.0, v157
	v_add_f32_e32 v159, 1.0, v159
	v_add_f32_e32 v163, 1.0, v163
	v_rcp_f32_e32 v151, v151
	v_rcp_f32_e32 v157, v157
	v_rcp_f32_e32 v159, v159
	v_add_f32_e32 v161, 1.0, v161
	v_rcp_f32_e32 v163, v163
	v_add_f32_e32 v165, 1.0, v165
	v_rcp_f32_e32 v161, v161
	v_rcp_f32_e32 v165, v165
	v_fma_f32 v147, v147, s31, 0.5
	v_fma_f32 v155, v155, s31, 0.5
	v_max_f32_e32 v147, 1.0, v147
	v_fma_f32 v151, v151, s31, 0.5
	v_max_f32_e32 v155, 1.0, v155
	v_fma_f32 v157, v157, s31, 0.5
	v_fma_f32 v159, v159, s31, 0.5
	v_fma_f32 v163, v163, s31, 0.5
	v_cvt_u32_f32_e32 v147, v147
	v_max_f32_e32 v151, 1.0, v151
	v_cvt_u32_f32_e32 v155, v155
	v_max_f32_e32 v157, 1.0, v157
	v_max_f32_e32 v159, 1.0, v159
	v_fma_f32 v161, v161, s31, 0.5
	v_max_f32_e32 v163, 1.0, v163
	v_fma_f32 v165, v165, s31, 0.5
	v_cvt_u32_f32_e32 v151, v151
	v_cvt_u32_f32_e32 v157, v157
	v_cvt_u32_f32_sdwa v159, v159 dst_sel:WORD_1 dst_unused:UNUSED_PAD src0_sel:DWORD
	v_max_f32_e32 v161, 1.0, v161
	v_cvt_u32_f32_sdwa v163, v163 dst_sel:BYTE_3 dst_unused:UNUSED_PAD src0_sel:DWORD
	v_max_f32_e32 v165, 1.0, v165
	v_cvt_u32_f32_sdwa v161, v161 dst_sel:WORD_1 dst_unused:UNUSED_PAD src0_sel:DWORD
	v_cvt_u32_f32_sdwa v165, v165 dst_sel:BYTE_3 dst_unused:UNUSED_PAD src0_sel:DWORD
	v_lshl_or_b32 v147, v155, 8, v147
	v_or3_b32 v176, v147, v159, v163
	v_lshl_or_b32 v147, v157, 8, v151
	v_or3_b32 v177, v147, v161, v165
	v_mul_f32_e32 v147, v18, v144
	v_mul_f32_e32 v155, v19, v144
	v_mul_f32_e32 v151, v8, v144
	v_mul_f32_e32 v157, v9, v144
	v_mul_f32_e32 v159, v20, v144
	v_mul_f32_e32 v163, v21, v144
	v_exp_f32_e32 v147, v147
	v_exp_f32_e32 v155, v155
	v_mul_f32_e32 v161, v10, v144
	v_mul_f32_e32 v165, v11, v144
	v_exp_f32_e32 v151, v151
	v_exp_f32_e32 v157, v157
	v_exp_f32_e32 v159, v159
	v_exp_f32_e32 v163, v163
	v_exp_f32_e32 v161, v161
	v_exp_f32_e32 v165, v165
	v_add_f32_e32 v147, 1.0, v147
	v_add_f32_e32 v155, 1.0, v155
	v_rcp_f32_e32 v147, v147
	v_add_f32_e32 v151, 1.0, v151
	v_rcp_f32_e32 v155, v155
	v_add_f32_e32 v157, 1.0, v157
	v_add_f32_e32 v159, 1.0, v159
	v_add_f32_e32 v163, 1.0, v163
	v_rcp_f32_e32 v151, v151
	v_rcp_f32_e32 v157, v157
	v_rcp_f32_e32 v159, v159
	v_add_f32_e32 v161, 1.0, v161
	v_rcp_f32_e32 v163, v163
	v_add_f32_e32 v165, 1.0, v165
	v_rcp_f32_e32 v161, v161
	v_rcp_f32_e32 v165, v165
	v_fma_f32 v147, v147, s31, 0.5
	v_fma_f32 v155, v155, s31, 0.5
	v_max_f32_e32 v147, 1.0, v147
	v_fma_f32 v151, v151, s31, 0.5
	v_max_f32_e32 v155, 1.0, v155
	v_fma_f32 v157, v157, s31, 0.5
	v_fma_f32 v159, v159, s31, 0.5
	v_fma_f32 v163, v163, s31, 0.5
	v_cvt_u32_f32_e32 v147, v147
	v_max_f32_e32 v151, 1.0, v151
	v_cvt_u32_f32_e32 v155, v155
	v_max_f32_e32 v157, 1.0, v157
	v_max_f32_e32 v159, 1.0, v159
	v_fma_f32 v161, v161, s31, 0.5
	v_max_f32_e32 v163, 1.0, v163
	v_fma_f32 v165, v165, s31, 0.5
	v_cvt_u32_f32_e32 v151, v151
	v_cvt_u32_f32_e32 v157, v157
	v_cvt_u32_f32_sdwa v159, v159 dst_sel:WORD_1 dst_unused:UNUSED_PAD src0_sel:DWORD
	v_max_f32_e32 v161, 1.0, v161
	v_cvt_u32_f32_sdwa v163, v163 dst_sel:BYTE_3 dst_unused:UNUSED_PAD src0_sel:DWORD
	v_max_f32_e32 v165, 1.0, v165
	v_cvt_u32_f32_sdwa v161, v161 dst_sel:WORD_1 dst_unused:UNUSED_PAD src0_sel:DWORD
	v_cvt_u32_f32_sdwa v165, v165 dst_sel:BYTE_3 dst_unused:UNUSED_PAD src0_sel:DWORD
	v_lshl_add_u64 v[174:175], s[22:23], 0, v[174:175]
	v_lshl_add_u64 v[174:175], v[174:175], 0, v[172:173]
	v_lshl_or_b32 v147, v155, 8, v147
	global_store_dwordx2 v[174:175], v[176:177], off
	v_or3_b32 v176, v147, v159, v163
	v_lshl_or_b32 v147, v157, 8, v151
	v_or3_b32 v177, v147, v161, v165
	global_store_dwordx2 v[174:175], v[176:177], off offset:128
	v_lshlrev_b64 v[174:175], 12, v[142:143]
	v_mul_f32_e32 v143, v22, v140
	v_mul_f32_e32 v151, v23, v140
	v_mul_f32_e32 v147, v12, v140
	v_mul_f32_e32 v155, v13, v140
	v_mul_f32_e32 v157, v24, v140
	v_mul_f32_e32 v161, v25, v140
	v_exp_f32_e32 v143, v143
	v_exp_f32_e32 v151, v151
	v_mul_f32_e32 v159, v14, v140
	v_mul_f32_e32 v163, v15, v140
	v_exp_f32_e32 v147, v147
	v_exp_f32_e32 v155, v155
	v_exp_f32_e32 v157, v157
	v_exp_f32_e32 v161, v161
	v_exp_f32_e32 v159, v159
	v_exp_f32_e32 v163, v163
	v_add_f32_e32 v143, 1.0, v143
	v_add_f32_e32 v151, 1.0, v151
	v_rcp_f32_e32 v143, v143
	v_add_f32_e32 v147, 1.0, v147
	v_rcp_f32_e32 v151, v151
	v_add_f32_e32 v155, 1.0, v155
	v_add_f32_e32 v157, 1.0, v157
	v_add_f32_e32 v161, 1.0, v161
	v_rcp_f32_e32 v147, v147
	v_rcp_f32_e32 v155, v155
	v_rcp_f32_e32 v157, v157
	v_add_f32_e32 v159, 1.0, v159
	v_rcp_f32_e32 v161, v161
	v_add_f32_e32 v163, 1.0, v163
	v_rcp_f32_e32 v159, v159
	v_rcp_f32_e32 v163, v163
	v_fma_f32 v143, v143, s31, 0.5
	v_fma_f32 v151, v151, s31, 0.5
	v_max_f32_e32 v143, 1.0, v143
	v_fma_f32 v147, v147, s31, 0.5
	v_max_f32_e32 v151, 1.0, v151
	v_fma_f32 v155, v155, s31, 0.5
	v_fma_f32 v157, v157, s31, 0.5
	v_fma_f32 v161, v161, s31, 0.5
	v_cvt_u32_f32_e32 v143, v143
	v_max_f32_e32 v147, 1.0, v147
	v_cvt_u32_f32_e32 v151, v151
	v_max_f32_e32 v155, 1.0, v155
	v_max_f32_e32 v157, 1.0, v157
	v_fma_f32 v159, v159, s31, 0.5
	v_max_f32_e32 v161, 1.0, v161
	v_fma_f32 v163, v163, s31, 0.5
	v_cvt_u32_f32_e32 v147, v147
	v_cvt_u32_f32_e32 v155, v155
	v_cvt_u32_f32_sdwa v157, v157 dst_sel:WORD_1 dst_unused:UNUSED_PAD src0_sel:DWORD
	v_max_f32_e32 v159, 1.0, v159
	v_cvt_u32_f32_sdwa v161, v161 dst_sel:BYTE_3 dst_unused:UNUSED_PAD src0_sel:DWORD
	v_max_f32_e32 v163, 1.0, v163
	v_cvt_u32_f32_sdwa v159, v159 dst_sel:WORD_1 dst_unused:UNUSED_PAD src0_sel:DWORD
	v_cvt_u32_f32_sdwa v163, v163 dst_sel:BYTE_3 dst_unused:UNUSED_PAD src0_sel:DWORD
	v_lshl_or_b32 v143, v151, 8, v143
	v_or3_b32 v176, v143, v157, v161
	v_lshl_or_b32 v143, v155, 8, v147
	v_or3_b32 v177, v143, v159, v163
	v_mul_f32_e32 v143, v4, v140
	v_mul_f32_e32 v151, v5, v140
	v_mul_f32_e32 v147, v0, v140
	v_mul_f32_e32 v155, v1, v140
	v_mul_f32_e32 v157, v6, v140
	v_mul_f32_e32 v161, v7, v140
	v_exp_f32_e32 v143, v143
	v_exp_f32_e32 v151, v151
	v_mul_f32_e32 v159, v2, v140
	v_mul_f32_e32 v163, v3, v140
	v_exp_f32_e32 v147, v147
	v_exp_f32_e32 v155, v155
	v_exp_f32_e32 v157, v157
	v_exp_f32_e32 v161, v161
	v_exp_f32_e32 v159, v159
	v_exp_f32_e32 v163, v163
	v_add_f32_e32 v143, 1.0, v143
	v_add_f32_e32 v151, 1.0, v151
	v_rcp_f32_e32 v143, v143
	v_add_f32_e32 v147, 1.0, v147
	v_rcp_f32_e32 v151, v151
	v_add_f32_e32 v155, 1.0, v155
	v_add_f32_e32 v157, 1.0, v157
	v_add_f32_e32 v161, 1.0, v161
	v_rcp_f32_e32 v147, v147
	v_rcp_f32_e32 v155, v155
	v_rcp_f32_e32 v157, v157
	v_add_f32_e32 v159, 1.0, v159
	v_rcp_f32_e32 v161, v161
	v_add_f32_e32 v163, 1.0, v163
	v_rcp_f32_e32 v159, v159
	v_rcp_f32_e32 v163, v163
	v_fma_f32 v143, v143, s31, 0.5
	v_fma_f32 v151, v151, s31, 0.5
	v_max_f32_e32 v143, 1.0, v143
	v_fma_f32 v147, v147, s31, 0.5
	v_max_f32_e32 v151, 1.0, v151
	v_fma_f32 v155, v155, s31, 0.5
	v_fma_f32 v157, v157, s31, 0.5
	v_fma_f32 v161, v161, s31, 0.5
	v_cvt_u32_f32_e32 v143, v143
	v_max_f32_e32 v147, 1.0, v147
	v_cvt_u32_f32_e32 v151, v151
	v_max_f32_e32 v155, 1.0, v155
	v_max_f32_e32 v157, 1.0, v157
	v_fma_f32 v159, v159, s31, 0.5
	v_max_f32_e32 v161, 1.0, v161
	v_fma_f32 v163, v163, s31, 0.5
	v_cvt_u32_f32_e32 v147, v147
	v_cvt_u32_f32_e32 v155, v155
	v_cvt_u32_f32_sdwa v157, v157 dst_sel:WORD_1 dst_unused:UNUSED_PAD src0_sel:DWORD
	v_max_f32_e32 v159, 1.0, v159
	v_cvt_u32_f32_sdwa v161, v161 dst_sel:BYTE_3 dst_unused:UNUSED_PAD src0_sel:DWORD
	v_max_f32_e32 v163, 1.0, v163
	v_cvt_u32_f32_sdwa v159, v159 dst_sel:WORD_1 dst_unused:UNUSED_PAD src0_sel:DWORD
	v_cvt_u32_f32_sdwa v163, v163 dst_sel:BYTE_3 dst_unused:UNUSED_PAD src0_sel:DWORD
	v_lshl_add_u64 v[174:175], s[22:23], 0, v[174:175]
	v_lshl_add_u64 v[174:175], v[174:175], 0, v[172:173]
	v_lshl_or_b32 v143, v151, 8, v143
	global_store_dwordx2 v[174:175], v[176:177], off
	v_or3_b32 v176, v143, v157, v161
	v_lshl_or_b32 v143, v155, 8, v147
	v_or3_b32 v177, v143, v159, v163
	s_mov_b64 s[22:23], 0
	global_store_dwordx2 v[174:175], v[176:177], off offset:128
	s_branch .LBB0_674

.LBB0_962:
	s_add_u32 s16, s12, 0xfffc0080
	s_addc_u32 s17, s13, -1
	s_add_i32 s33, 0, 0x10000
	v_add_u32_e32 v148, s33, v151
	ds_read_b128 v[140:143], v148
	ds_read_b128 v[144:147], v148 offset:1024
	ds_read_b128 v[154:157], v148 offset:2048
	ds_read_b128 v[158:161], v148 offset:3072
	s_cmp_eq_u32 s25, 12
	s_cselect_b32 s23, s9, s17
	s_cselect_b32 s22, s8, s16
	s_cselect_b32 s17, s11, s7
	s_cselect_b32 s16, s10, s5
	v_lshl_add_u64 v[148:149], s[12:13], 0, v[136:137]
	s_add_i32 m0, s38, 0xc000
	ds_read_b128 v[162:165], v153
	ds_read_b128 v[166:169], v153 offset:1024
	ds_read_b128 v[170:173], v153 offset:2048
	ds_read_b128 v[174:177], v153 offset:3072
	ds_read_b128 v[188:191], v153 offset:4096
	ds_read_b128 v[192:195], v153 offset:5120
	ds_read_b128 v[196:199], v153 offset:6144
	ds_read_b128 v[200:203], v153 offset:7168
	global_load_lds_dwordx4 v[148:149], off
	v_lshl_add_u64 v[148:149], s[12:13], 0, v[138:139]
	s_add_i32 m0, s38, 0xe000
	s_nop 0
	global_load_lds_dwordx4 v[148:149], off
	s_waitcnt lgkmcnt(8)
	s_barrier
	s_waitcnt lgkmcnt(0)
	s_setprio 1
	s_waitcnt lgkmcnt(0)
	v_mfma_f32_16x16x32_bf16 v[126:129], v[140:143], v[162:165], v[126:129]
	v_mfma_f32_16x16x32_bf16 v[122:125], v[154:157], v[162:165], v[122:125]
	v_mfma_f32_16x16x32_bf16 v[110:113], v[140:143], v[170:173], v[110:113]
	v_mfma_f32_16x16x32_bf16 v[106:109], v[154:157], v[170:173], v[106:109]
	v_mfma_f32_16x16x32_bf16 v[94:97], v[140:143], v[188:191], v[94:97]
	v_mfma_f32_16x16x32_bf16 v[90:93], v[154:157], v[188:191], v[90:93]
	v_mfma_f32_16x16x32_bf16 v[78:81], v[140:143], v[196:199], v[78:81]
	v_mfma_f32_16x16x32_bf16 v[74:77], v[154:157], v[196:199], v[74:77]
	v_mfma_f32_16x16x32_bf16 v[126:129], v[144:147], v[166:169], v[126:129]
	v_mfma_f32_16x16x32_bf16 v[122:125], v[158:161], v[166:169], v[122:125]
	v_mfma_f32_16x16x32_bf16 v[110:113], v[144:147], v[174:177], v[110:113]
	v_mfma_f32_16x16x32_bf16 v[106:109], v[158:161], v[174:177], v[106:109]
	v_mfma_f32_16x16x32_bf16 v[94:97], v[144:147], v[192:195], v[94:97]
	v_mfma_f32_16x16x32_bf16 v[90:93], v[158:161], v[192:195], v[90:93]
	v_mfma_f32_16x16x32_bf16 v[78:81], v[144:147], v[200:203], v[78:81]
	v_mfma_f32_16x16x32_bf16 v[74:77], v[158:161], v[200:203], v[74:77]
	s_setprio 0
	s_barrier
	s_add_i32 s45, 0, 0x14000
	v_add_u32_e32 v148, s45, v151
	s_add_i32 s33, s33, s35
	ds_read_b128 v[204:207], v148
	ds_read_b128 v[208:211], v148 offset:1024
	ds_read_b128 v[212:215], v148 offset:2048
	ds_read_b128 v[216:219], v148 offset:3072
	v_lshl_add_u64 v[148:149], s[16:17], 0, v[16:17]
	s_mov_b32 m0, s33
	v_lshl_add_u64 v[178:179], s[16:17], 0, v[130:131]
	global_load_lds_dwordx4 v[148:149], off
	s_add_i32 m0, s33, 0x2000
	s_nop 0
	global_load_lds_dwordx4 v[178:179], off
	s_barrier
	s_waitcnt lgkmcnt(0)
	s_setprio 1
	s_waitcnt lgkmcnt(0)
	v_mfma_f32_16x16x32_bf16 v[118:121], v[204:207], v[162:165], v[118:121]
	v_mfma_f32_16x16x32_bf16 v[114:117], v[212:215], v[162:165], v[114:117]
	v_mfma_f32_16x16x32_bf16 v[102:105], v[204:207], v[170:173], v[102:105]
	v_mfma_f32_16x16x32_bf16 v[98:101], v[212:215], v[170:173], v[98:101]
	v_mfma_f32_16x16x32_bf16 v[86:89], v[204:207], v[188:191], v[86:89]
	v_mfma_f32_16x16x32_bf16 v[82:85], v[212:215], v[188:191], v[82:85]
	v_mfma_f32_16x16x32_bf16 v[70:73], v[204:207], v[196:199], v[70:73]
	v_mfma_f32_16x16x32_bf16 v[66:69], v[212:215], v[196:199], v[66:69]
	v_mfma_f32_16x16x32_bf16 v[118:121], v[208:211], v[166:169], v[118:121]
	v_mfma_f32_16x16x32_bf16 v[114:117], v[216:219], v[166:169], v[114:117]
	v_mfma_f32_16x16x32_bf16 v[102:105], v[208:211], v[174:177], v[102:105]
	v_mfma_f32_16x16x32_bf16 v[98:101], v[216:219], v[174:177], v[98:101]
	v_mfma_f32_16x16x32_bf16 v[86:89], v[208:211], v[192:195], v[86:89]
	v_mfma_f32_16x16x32_bf16 v[82:85], v[216:219], v[192:195], v[82:85]
	v_mfma_f32_16x16x32_bf16 v[70:73], v[208:211], v[200:203], v[70:73]
	v_mfma_f32_16x16x32_bf16 v[66:69], v[216:219], v[200:203], v[66:69]
	s_setprio 0
	s_mov_b32 m0, s38
	v_lshl_add_u64 v[180:181], s[22:23], 0, v[134:135]
	s_barrier
	ds_read_b128 v[162:165], v153 offset:16384
	ds_read_b128 v[166:169], v153 offset:17408
	ds_read_b128 v[170:173], v153 offset:18432
	ds_read_b128 v[174:177], v153 offset:19456
	ds_read_b128 v[188:191], v153 offset:20480
	ds_read_b128 v[192:195], v153 offset:21504
	ds_read_b128 v[196:199], v153 offset:22528
	ds_read_b128 v[200:203], v153 offset:23552
	global_load_lds_dwordx4 v[180:181], off
	v_lshl_add_u64 v[220:221], s[22:23], 0, v[132:133]
	s_mov_b32 m0, s39
	s_nop 0
	global_load_lds_dwordx4 v[220:221], off
	s_barrier
	s_waitcnt lgkmcnt(0)
	s_setprio 1
	s_waitcnt lgkmcnt(0)
	v_mfma_f32_16x16x32_bf16 v[62:65], v[140:143], v[162:165], v[62:65]
	v_mfma_f32_16x16x32_bf16 v[58:61], v[154:157], v[162:165], v[58:61]
	v_mfma_f32_16x16x32_bf16 v[46:49], v[140:143], v[170:173], v[46:49]
	v_mfma_f32_16x16x32_bf16 v[42:45], v[154:157], v[170:173], v[42:45]
	v_mfma_f32_16x16x32_bf16 v[30:33], v[140:143], v[188:191], v[30:33]
	v_mfma_f32_16x16x32_bf16 v[26:29], v[154:157], v[188:191], v[26:29]
	v_mfma_f32_16x16x32_bf16 v[12:15], v[140:143], v[196:199], v[12:15]
	v_mfma_f32_16x16x32_bf16 v[8:11], v[154:157], v[196:199], v[8:11]
	v_mfma_f32_16x16x32_bf16 v[62:65], v[144:147], v[166:169], v[62:65]
	v_mfma_f32_16x16x32_bf16 v[58:61], v[158:161], v[166:169], v[58:61]
	v_mfma_f32_16x16x32_bf16 v[46:49], v[144:147], v[174:177], v[46:49]
	v_mfma_f32_16x16x32_bf16 v[42:45], v[158:161], v[174:177], v[42:45]
	v_mfma_f32_16x16x32_bf16 v[30:33], v[144:147], v[192:195], v[30:33]
	v_mfma_f32_16x16x32_bf16 v[26:29], v[158:161], v[192:195], v[26:29]
	v_mfma_f32_16x16x32_bf16 v[12:15], v[144:147], v[200:203], v[12:15]
	v_mfma_f32_16x16x32_bf16 v[8:11], v[158:161], v[200:203], v[8:11]
	s_setprio 0
	s_barrier
	s_add_u32 s46, s16, 0x40000
	s_addc_u32 s47, s17, 0
	s_add_i32 s33, s45, s35
	v_lshl_add_u64 v[140:141], s[46:47], 0, v[16:17]
	s_mov_b32 m0, s33
	s_nop 0
	global_load_lds_dwordx4 v[140:141], off
	v_lshl_add_u64 v[140:141], s[46:47], 0, v[130:131]
	s_add_i32 m0, s33, 0x2000
	s_nop 0
	global_load_lds_dwordx4 v[140:141], off
	s_waitcnt vmcnt(6)
	s_barrier
	s_setprio 1
	v_mfma_f32_16x16x32_bf16 v[54:57], v[204:207], v[162:165], v[54:57]
	v_mfma_f32_16x16x32_bf16 v[50:53], v[212:215], v[162:165], v[50:53]
	v_mfma_f32_16x16x32_bf16 v[38:41], v[204:207], v[170:173], v[38:41]
	v_mfma_f32_16x16x32_bf16 v[34:37], v[212:215], v[170:173], v[34:37]
	v_mfma_f32_16x16x32_bf16 v[22:25], v[204:207], v[188:191], v[22:25]
	v_mfma_f32_16x16x32_bf16 v[18:21], v[212:215], v[188:191], v[18:21]
	v_mfma_f32_16x16x32_bf16 v[4:7], v[204:207], v[196:199], v[4:7]
	v_mfma_f32_16x16x32_bf16 v[0:3], v[212:215], v[196:199], v[0:3]
	v_mfma_f32_16x16x32_bf16 v[54:57], v[208:211], v[166:169], v[54:57]
	v_mfma_f32_16x16x32_bf16 v[50:53], v[216:219], v[166:169], v[50:53]
	v_mfma_f32_16x16x32_bf16 v[38:41], v[208:211], v[174:177], v[38:41]
	v_mfma_f32_16x16x32_bf16 v[34:37], v[216:219], v[174:177], v[34:37]
	v_mfma_f32_16x16x32_bf16 v[22:25], v[208:211], v[192:195], v[22:25]
	v_mfma_f32_16x16x32_bf16 v[18:21], v[216:219], v[192:195], v[18:21]
	v_mfma_f32_16x16x32_bf16 v[4:7], v[208:211], v[200:203], v[4:7]
	v_mfma_f32_16x16x32_bf16 v[0:3], v[216:219], v[200:203], v[0:3]
	s_setprio 0
	s_add_i32 s33, 0, 0x18000
	v_add_u32_e32 v158, s33, v151
	s_barrier
	ds_read_b128 v[140:143], v158
	ds_read_b128 v[144:147], v158 offset:1024
	ds_read_b128 v[154:157], v158 offset:2048
	ds_read_b128 v[158:161], v158 offset:3072
	s_add_u32 s22, s22, 0x40000
	s_addc_u32 s23, s23, 0
	s_mov_b32 m0, s40
	v_lshl_add_u64 v[204:205], s[22:23], 0, v[134:135]
	ds_read_b128 v[162:165], v153 offset:32768
	ds_read_b128 v[166:169], v153 offset:33792
	ds_read_b128 v[170:173], v153 offset:34816
	ds_read_b128 v[174:177], v153 offset:35840
	ds_read_b128 v[188:191], v153 offset:36864
	ds_read_b128 v[192:195], v153 offset:37888
	ds_read_b128 v[196:199], v153 offset:38912
	ds_read_b128 v[200:203], v153 offset:39936
	global_load_lds_dwordx4 v[204:205], off
	v_lshl_add_u64 v[204:205], s[22:23], 0, v[132:133]
	s_mov_b32 m0, s41
	s_nop 0
	global_load_lds_dwordx4 v[204:205], off
	s_waitcnt lgkmcnt(8)
	s_barrier
	s_waitcnt lgkmcnt(0)
	s_setprio 1
	s_waitcnt lgkmcnt(0)
	v_mfma_f32_16x16x32_bf16 v[126:129], v[140:143], v[162:165], v[126:129]
	v_mfma_f32_16x16x32_bf16 v[122:125], v[154:157], v[162:165], v[122:125]
	v_mfma_f32_16x16x32_bf16 v[110:113], v[140:143], v[170:173], v[110:113]
	v_mfma_f32_16x16x32_bf16 v[106:109], v[154:157], v[170:173], v[106:109]
	v_mfma_f32_16x16x32_bf16 v[94:97], v[140:143], v[188:191], v[94:97]
	v_mfma_f32_16x16x32_bf16 v[90:93], v[154:157], v[188:191], v[90:93]
	v_mfma_f32_16x16x32_bf16 v[78:81], v[140:143], v[196:199], v[78:81]
	v_mfma_f32_16x16x32_bf16 v[74:77], v[154:157], v[196:199], v[74:77]
	v_mfma_f32_16x16x32_bf16 v[126:129], v[144:147], v[166:169], v[126:129]
	v_mfma_f32_16x16x32_bf16 v[122:125], v[158:161], v[166:169], v[122:125]
	v_mfma_f32_16x16x32_bf16 v[110:113], v[144:147], v[174:177], v[110:113]
	v_mfma_f32_16x16x32_bf16 v[106:109], v[158:161], v[174:177], v[106:109]
	v_mfma_f32_16x16x32_bf16 v[94:97], v[144:147], v[192:195], v[94:97]
	v_mfma_f32_16x16x32_bf16 v[90:93], v[158:161], v[192:195], v[90:93]
	v_mfma_f32_16x16x32_bf16 v[78:81], v[144:147], v[200:203], v[78:81]
	v_mfma_f32_16x16x32_bf16 v[74:77], v[158:161], v[200:203], v[74:77]
	s_setprio 0
	s_barrier
	s_add_i32 s22, 0, 0x1c000
	s_add_i32 s23, s33, s35
	v_add_u32_e32 v183, s22, v151
	v_lshl_add_u64 v[148:149], v[148:149], 0, s[14:15]
	s_mov_b32 m0, s23
	ds_read_b128 v[204:207], v183
	ds_read_b128 v[208:211], v183 offset:1024
	ds_read_b128 v[212:215], v183 offset:2048
	ds_read_b128 v[216:219], v183 offset:3072
	global_load_lds_dwordx4 v[148:149], off
	v_lshl_add_u64 v[148:149], v[178:179], 0, s[14:15]
	s_add_i32 m0, s23, 0x2000
	s_nop 0
	global_load_lds_dwordx4 v[148:149], off
	s_barrier
	s_waitcnt lgkmcnt(0)
	s_setprio 1
	s_waitcnt lgkmcnt(0)
	v_mfma_f32_16x16x32_bf16 v[118:121], v[204:207], v[162:165], v[118:121]
	v_mfma_f32_16x16x32_bf16 v[114:117], v[212:215], v[162:165], v[114:117]
	v_mfma_f32_16x16x32_bf16 v[102:105], v[204:207], v[170:173], v[102:105]
	v_mfma_f32_16x16x32_bf16 v[98:101], v[212:215], v[170:173], v[98:101]
	v_mfma_f32_16x16x32_bf16 v[86:89], v[204:207], v[188:191], v[86:89]
	v_mfma_f32_16x16x32_bf16 v[82:85], v[212:215], v[188:191], v[82:85]
	v_mfma_f32_16x16x32_bf16 v[70:73], v[204:207], v[196:199], v[70:73]
	v_mfma_f32_16x16x32_bf16 v[66:69], v[212:215], v[196:199], v[66:69]
	v_mfma_f32_16x16x32_bf16 v[118:121], v[208:211], v[166:169], v[118:121]
	v_mfma_f32_16x16x32_bf16 v[114:117], v[216:219], v[166:169], v[114:117]
	v_mfma_f32_16x16x32_bf16 v[102:105], v[208:211], v[174:177], v[102:105]
	v_mfma_f32_16x16x32_bf16 v[98:101], v[216:219], v[174:177], v[98:101]
	v_mfma_f32_16x16x32_bf16 v[86:89], v[208:211], v[192:195], v[86:89]
	v_mfma_f32_16x16x32_bf16 v[82:85], v[216:219], v[192:195], v[82:85]
	v_mfma_f32_16x16x32_bf16 v[70:73], v[208:211], v[200:203], v[70:73]
	v_mfma_f32_16x16x32_bf16 v[66:69], v[216:219], v[200:203], v[66:69]
	s_setprio 0
	s_mov_b32 m0, s42
	v_lshl_add_u64 v[148:149], v[180:181], 0, s[14:15]
	s_barrier
	ds_read_b128 v[162:165], v153 offset:49152
	ds_read_b128 v[166:169], v153 offset:50176
	ds_read_b128 v[170:173], v153 offset:51200
	ds_read_b128 v[174:177], v153 offset:52224
	ds_read_b128 v[188:191], v153 offset:53248
	ds_read_b128 v[192:195], v153 offset:54272
	ds_read_b128 v[196:199], v153 offset:55296
	ds_read_b128 v[200:203], v153 offset:56320
	global_load_lds_dwordx4 v[148:149], off
	v_lshl_add_u64 v[148:149], v[220:221], 0, s[14:15]
	s_mov_b32 m0, s43
	s_nop 0
	global_load_lds_dwordx4 v[148:149], off
	s_barrier
	s_waitcnt lgkmcnt(0)
	s_setprio 1
	s_waitcnt lgkmcnt(0)
	v_mfma_f32_16x16x32_bf16 v[62:65], v[140:143], v[162:165], v[62:65]
	v_mfma_f32_16x16x32_bf16 v[58:61], v[154:157], v[162:165], v[58:61]
	v_mfma_f32_16x16x32_bf16 v[46:49], v[140:143], v[170:173], v[46:49]
	v_mfma_f32_16x16x32_bf16 v[42:45], v[154:157], v[170:173], v[42:45]
	v_mfma_f32_16x16x32_bf16 v[30:33], v[140:143], v[188:191], v[30:33]
	v_mfma_f32_16x16x32_bf16 v[26:29], v[154:157], v[188:191], v[26:29]
	v_mfma_f32_16x16x32_bf16 v[12:15], v[140:143], v[196:199], v[12:15]
	v_mfma_f32_16x16x32_bf16 v[8:11], v[154:157], v[196:199], v[8:11]
	v_mfma_f32_16x16x32_bf16 v[62:65], v[144:147], v[166:169], v[62:65]
	v_mfma_f32_16x16x32_bf16 v[58:61], v[158:161], v[166:169], v[58:61]
	v_mfma_f32_16x16x32_bf16 v[46:49], v[144:147], v[174:177], v[46:49]
	v_mfma_f32_16x16x32_bf16 v[42:45], v[158:161], v[174:177], v[42:45]
	v_mfma_f32_16x16x32_bf16 v[30:33], v[144:147], v[192:195], v[30:33]
	v_mfma_f32_16x16x32_bf16 v[26:29], v[158:161], v[192:195], v[26:29]
	v_mfma_f32_16x16x32_bf16 v[12:15], v[144:147], v[200:203], v[12:15]
	v_mfma_f32_16x16x32_bf16 v[8:11], v[158:161], v[200:203], v[8:11]
	s_setprio 0
	s_barrier
	s_add_u32 s16, s16, 0x40080
	s_addc_u32 s17, s17, 0
	s_add_i32 s22, s22, s35
	v_lshl_add_u64 v[140:141], s[16:17], 0, v[16:17]
	s_mov_b32 m0, s22
	s_nop 0
	global_load_lds_dwordx4 v[140:141], off
	v_lshl_add_u64 v[140:141], s[16:17], 0, v[130:131]
	s_add_i32 m0, s22, 0x2000
	s_nop 0
	global_load_lds_dwordx4 v[140:141], off
	s_waitcnt vmcnt(6)
	s_barrier
	s_setprio 1
	v_mfma_f32_16x16x32_bf16 v[54:57], v[204:207], v[162:165], v[54:57]
	v_mfma_f32_16x16x32_bf16 v[50:53], v[212:215], v[162:165], v[50:53]
	v_mfma_f32_16x16x32_bf16 v[38:41], v[204:207], v[170:173], v[38:41]
	v_mfma_f32_16x16x32_bf16 v[34:37], v[212:215], v[170:173], v[34:37]
	v_mfma_f32_16x16x32_bf16 v[22:25], v[204:207], v[188:191], v[22:25]
	v_mfma_f32_16x16x32_bf16 v[18:21], v[212:215], v[188:191], v[18:21]
	v_mfma_f32_16x16x32_bf16 v[4:7], v[204:207], v[196:199], v[4:7]
	v_mfma_f32_16x16x32_bf16 v[0:3], v[212:215], v[196:199], v[0:3]
	v_mfma_f32_16x16x32_bf16 v[54:57], v[208:211], v[166:169], v[54:57]
	v_mfma_f32_16x16x32_bf16 v[50:53], v[216:219], v[166:169], v[50:53]
	v_mfma_f32_16x16x32_bf16 v[38:41], v[208:211], v[174:177], v[38:41]
	v_mfma_f32_16x16x32_bf16 v[34:37], v[216:219], v[174:177], v[34:37]
	v_mfma_f32_16x16x32_bf16 v[22:25], v[208:211], v[192:195], v[22:25]
	v_mfma_f32_16x16x32_bf16 v[18:21], v[216:219], v[192:195], v[18:21]
	v_mfma_f32_16x16x32_bf16 v[4:7], v[208:211], v[200:203], v[4:7]
	v_mfma_f32_16x16x32_bf16 v[0:3], v[216:219], v[200:203], v[0:3]
	s_setprio 0
	s_add_i32 s25, s25, 2
	s_add_u32 s12, s12, 0x100
	s_addc_u32 s13, s13, 0
	s_add_u32 s5, s5, 0x100
	s_addc_u32 s7, s7, 0
	s_cmp_gt_u32 s25, 13
	s_barrier
	s_cbranch_scc0 .LBB0_962
	v_lshl_add_u32 v140, s21, 8, v150
	v_readlane_b32 s12, v252, 38
	v_ashrrev_i32_e32 v141, 31, v140
	v_readlane_b32 s13, v252, 39
	v_or_b32_e32 v148, 16, v140
	v_ashrrev_i32_e32 v149, 31, v148
	v_lshl_add_u64 v[144:145], v[140:141], 2, s[12:13]
	global_load_dword v161, v[144:145], off
	v_lshl_add_u64 v[142:143], v[148:149], 2, s[12:13]
	global_load_dword v160, v[142:143], off
	v_or_b32_e32 v146, 32, v140
	v_ashrrev_i32_e32 v147, 31, v146
	v_lshl_add_u64 v[142:143], v[146:147], 2, s[12:13]
	global_load_dword v159, v[142:143], off
	v_or_b32_e32 v142, 48, v140
	v_ashrrev_i32_e32 v143, 31, v142
	v_lshl_add_u64 v[154:155], v[142:143], 2, s[12:13]
	global_load_dword v158, v[154:155], off
	global_load_dword v157, v[144:145], off offset:512
	global_load_dword v156, v[144:145], off offset:576
	s_nop 0
	global_load_dword v155, v[144:145], off offset:640
	global_load_dword v154, v[144:145], off offset:704
	v_readlane_b32 s12, v252, 34
	v_lshl_or_b32 v144, s20, 8, v152
	v_lshlrev_b64 v[140:141], 12, v[140:141]
	v_readlane_b32 s13, v252, 35
	v_ashrrev_i32_e32 v145, 31, v144
	s_mov_b32 s5, 0x80000
	v_lshl_add_u64 v[140:141], s[12:13], 0, v[140:141]
	v_lshl_add_u64 v[140:141], v[140:141], 0, v[144:145]
	s_mov_b32 s21, s6
	s_mov_b32 s20, s4
	s_mov_b64 s[16:17], s[10:11]
	s_waitcnt vmcnt(0)
	v_mul_f32_e32 v161, 0xbfb8aa3b, v161
	v_mul_f32_e32 v160, 0xbfb8aa3b, v160
	v_mul_f32_e32 v159, 0xbfb8aa3b, v159
	v_mul_f32_e32 v158, 0xbfb8aa3b, v158
	v_mul_f32_e32 v157, 0xbfb8aa3b, v157
	v_mul_f32_e32 v156, 0xbfb8aa3b, v156
	v_mul_f32_e32 v155, 0xbfb8aa3b, v155
	v_mul_f32_e32 v154, 0xbfb8aa3b, v154
	v_mul_f32_e32 v122, v122, v161
	v_exp_f32_e32 v122, v122
	v_mul_f32_e32 v126, v126, v161
	v_mul_f32_e32 v123, v123, v161
	v_add_f32_e32 v122, 1.0, v122
	v_rcp_f32_e32 v122, v122
	v_mul_f32_e32 v124, v124, v161
	v_mul_f32_e32 v125, v125, v161
	v_fma_f32 v122, v122, s31, 0.5
	v_max_f32_e32 v122, 1.0, v122
	v_cvt_u32_f32_e32 v162, v122
	v_mul_f32_e32 v122, v127, v161
	v_mul_f32_e32 v127, v128, v161
	v_mul_f32_e32 v128, v129, v161
	v_exp_f32_e32 v126, v126
	v_exp_f32_e32 v122, v122
	v_exp_f32_e32 v123, v123
	v_exp_f32_e32 v127, v127
	v_exp_f32_e32 v124, v124
	v_exp_f32_e32 v128, v128
	v_exp_f32_e32 v125, v125
	v_add_f32_e32 v126, 1.0, v126
	v_add_f32_e32 v122, 1.0, v122
	v_add_f32_e32 v123, 1.0, v123
	v_mul_f32_e32 v114, v114, v161
	v_mul_f32_e32 v115, v115, v161
	v_rcp_f32_e32 v126, v126
	v_rcp_f32_e32 v122, v122
	v_rcp_f32_e32 v123, v123
	v_add_f32_e32 v127, 1.0, v127
	v_add_f32_e32 v124, 1.0, v124
	v_add_f32_e32 v128, 1.0, v128
	v_add_f32_e32 v125, 1.0, v125
	v_mul_f32_e32 v116, v116, v161
	v_mul_f32_e32 v117, v117, v161
	v_rcp_f32_e32 v127, v127
	v_rcp_f32_e32 v124, v124
	v_rcp_f32_e32 v128, v128
	v_rcp_f32_e32 v125, v125
	v_exp_f32_e32 v114, v114
	v_exp_f32_e32 v115, v115
	v_exp_f32_e32 v116, v116
	v_exp_f32_e32 v117, v117
	v_fma_f32 v126, v126, s31, 0.5
	v_fma_f32 v122, v122, s31, 0.5
	v_fma_f32 v123, v123, s31, 0.5
	v_mul_f32_e32 v106, v106, v160
	v_max_f32_e32 v126, 1.0, v126
	v_max_f32_e32 v122, 1.0, v122
	v_max_f32_e32 v123, 1.0, v123
	v_fma_f32 v127, v127, s31, 0.5
	v_fma_f32 v124, v124, s31, 0.5
	v_fma_f32 v128, v128, s31, 0.5
	v_fma_f32 v125, v125, s31, 0.5
	v_add_f32_e32 v114, 1.0, v114
	v_add_f32_e32 v115, 1.0, v115
	v_cvt_u32_f32_e32 v126, v126
	v_cvt_u32_f32_e32 v122, v122
	v_cvt_u32_f32_e32 v123, v123
	v_max_f32_e32 v127, 1.0, v127
	v_max_f32_e32 v124, 1.0, v124
	v_max_f32_e32 v128, 1.0, v128
	v_max_f32_e32 v125, 1.0, v125
	v_rcp_f32_e32 v114, v114
	v_rcp_f32_e32 v115, v115
	v_add_f32_e32 v116, 1.0, v116
	v_add_f32_e32 v117, 1.0, v117
	v_exp_f32_e32 v106, v106
	v_cvt_u32_f32_sdwa v127, v127 dst_sel:WORD_1 dst_unused:UNUSED_PAD src0_sel:DWORD
	v_cvt_u32_f32_sdwa v124, v124 dst_sel:WORD_1 dst_unused:UNUSED_PAD src0_sel:DWORD
	v_cvt_u32_f32_sdwa v128, v128 dst_sel:BYTE_3 dst_unused:UNUSED_PAD src0_sel:DWORD
	v_cvt_u32_f32_sdwa v125, v125 dst_sel:BYTE_3 dst_unused:UNUSED_PAD src0_sel:DWORD
	v_rcp_f32_e32 v116, v116
	v_rcp_f32_e32 v117, v117
	v_lshl_or_b32 v122, v122, 8, v126
	v_lshl_or_b32 v123, v123, 8, v162
	v_fma_f32 v114, v114, s31, 0.5
	v_fma_f32 v115, v115, s31, 0.5
	v_add_f32_e32 v106, 1.0, v106
	v_or3_b32 v122, v122, v127, v128
	v_or3_b32 v123, v123, v124, v125
	v_max_f32_e32 v114, 1.0, v114
	v_max_f32_e32 v115, 1.0, v115
	v_fma_f32 v116, v116, s31, 0.5
	v_fma_f32 v117, v117, s31, 0.5
	v_rcp_f32_e32 v106, v106
	global_store_dwordx2 v[140:141], v[122:123], off
	v_cvt_u32_f32_e32 v122, v114
	v_cvt_u32_f32_e32 v115, v115
	v_max_f32_e32 v116, 1.0, v116
	v_max_f32_e32 v117, 1.0, v117
	v_cvt_u32_f32_sdwa v116, v116 dst_sel:WORD_1 dst_unused:UNUSED_PAD src0_sel:DWORD
	v_cvt_u32_f32_sdwa v117, v117 dst_sel:BYTE_3 dst_unused:UNUSED_PAD src0_sel:DWORD
	v_mul_f32_e32 v118, v118, v161
	v_mul_f32_e32 v114, v119, v161
	v_mul_f32_e32 v119, v120, v161
	v_mul_f32_e32 v120, v121, v161
	v_fma_f32 v106, v106, s31, 0.5
	v_exp_f32_e32 v118, v118
	v_exp_f32_e32 v114, v114
	v_lshl_or_b32 v115, v115, 8, v122
	v_max_f32_e32 v106, 1.0, v106
	v_exp_f32_e32 v119, v119
	v_exp_f32_e32 v120, v120
	v_or3_b32 v115, v115, v116, v117
	v_mul_f32_e32 v110, v110, v160
	v_cvt_u32_f32_e32 v116, v106
	v_mul_f32_e32 v106, v111, v160
	v_mul_f32_e32 v107, v107, v160
	v_mul_f32_e32 v111, v112, v160
	v_mul_f32_e32 v108, v108, v160
	v_mul_f32_e32 v112, v113, v160
	v_mul_f32_e32 v109, v109, v160
	v_exp_f32_e32 v110, v110
	v_exp_f32_e32 v106, v106
	v_exp_f32_e32 v107, v107
	v_add_f32_e32 v118, 1.0, v118
	v_add_f32_e32 v114, 1.0, v114
	v_exp_f32_e32 v111, v111
	v_exp_f32_e32 v108, v108
	v_exp_f32_e32 v112, v112
	v_exp_f32_e32 v109, v109
	v_rcp_f32_e32 v118, v118
	v_rcp_f32_e32 v114, v114
	v_add_f32_e32 v119, 1.0, v119
	v_add_f32_e32 v120, 1.0, v120
	v_rcp_f32_e32 v119, v119
	v_rcp_f32_e32 v120, v120
	v_add_f32_e32 v110, 1.0, v110
	v_add_f32_e32 v106, 1.0, v106
	v_add_f32_e32 v107, 1.0, v107
	v_mul_f32_e32 v98, v98, v160
	v_mul_f32_e32 v99, v99, v160
	v_rcp_f32_e32 v110, v110
	v_rcp_f32_e32 v106, v106
	v_rcp_f32_e32 v107, v107
	v_add_f32_e32 v111, 1.0, v111
	v_add_f32_e32 v108, 1.0, v108
	v_add_f32_e32 v112, 1.0, v112
	v_add_f32_e32 v109, 1.0, v109
	v_mul_f32_e32 v100, v100, v160
	v_mul_f32_e32 v101, v101, v160
	v_fma_f32 v118, v118, s31, 0.5
	v_fma_f32 v114, v114, s31, 0.5
	v_rcp_f32_e32 v111, v111
	v_rcp_f32_e32 v108, v108
	v_rcp_f32_e32 v112, v112
	v_rcp_f32_e32 v109, v109
	v_exp_f32_e32 v98, v98
	v_exp_f32_e32 v99, v99
	v_max_f32_e32 v118, 1.0, v118
	v_max_f32_e32 v114, 1.0, v114
	v_fma_f32 v119, v119, s31, 0.5
	v_fma_f32 v120, v120, s31, 0.5
	v_exp_f32_e32 v100, v100
	v_exp_f32_e32 v101, v101
	v_cvt_u32_f32_e32 v118, v118
	v_cvt_u32_f32_e32 v114, v114
	v_max_f32_e32 v119, 1.0, v119
	v_max_f32_e32 v120, 1.0, v120
	v_cvt_u32_f32_sdwa v119, v119 dst_sel:WORD_1 dst_unused:UNUSED_PAD src0_sel:DWORD
	v_cvt_u32_f32_sdwa v120, v120 dst_sel:BYTE_3 dst_unused:UNUSED_PAD src0_sel:DWORD
	v_fma_f32 v110, v110, s31, 0.5
	v_fma_f32 v106, v106, s31, 0.5
	v_fma_f32 v107, v107, s31, 0.5
	v_mul_f32_e32 v90, v90, v159
	v_max_f32_e32 v110, 1.0, v110
	v_max_f32_e32 v106, 1.0, v106
	v_max_f32_e32 v107, 1.0, v107
	v_fma_f32 v111, v111, s31, 0.5
	v_fma_f32 v108, v108, s31, 0.5
	v_fma_f32 v112, v112, s31, 0.5
	v_fma_f32 v109, v109, s31, 0.5
	v_add_f32_e32 v98, 1.0, v98
	v_add_f32_e32 v99, 1.0, v99
	v_cvt_u32_f32_e32 v110, v110
	v_cvt_u32_f32_e32 v106, v106
	v_cvt_u32_f32_e32 v107, v107
	v_max_f32_e32 v111, 1.0, v111
	v_max_f32_e32 v108, 1.0, v108
	v_max_f32_e32 v112, 1.0, v112
	v_max_f32_e32 v109, 1.0, v109
	v_rcp_f32_e32 v98, v98
	v_rcp_f32_e32 v99, v99
	v_add_f32_e32 v100, 1.0, v100
	v_add_f32_e32 v101, 1.0, v101
	v_exp_f32_e32 v90, v90
	v_lshl_or_b32 v114, v114, 8, v118
	v_cvt_u32_f32_sdwa v111, v111 dst_sel:WORD_1 dst_unused:UNUSED_PAD src0_sel:DWORD
	v_cvt_u32_f32_sdwa v108, v108 dst_sel:WORD_1 dst_unused:UNUSED_PAD src0_sel:DWORD
	v_cvt_u32_f32_sdwa v112, v112 dst_sel:BYTE_3 dst_unused:UNUSED_PAD src0_sel:DWORD
	v_cvt_u32_f32_sdwa v109, v109 dst_sel:BYTE_3 dst_unused:UNUSED_PAD src0_sel:DWORD
	v_rcp_f32_e32 v100, v100
	v_rcp_f32_e32 v101, v101
	v_or3_b32 v114, v114, v119, v120
	global_store_dwordx2 v[140:141], v[114:115], off offset:128
	v_lshlrev_b64 v[114:115], 12, v[148:149]
	v_lshl_add_u64 v[114:115], s[12:13], 0, v[114:115]
	v_lshl_or_b32 v106, v106, 8, v110
	v_lshl_or_b32 v107, v107, 8, v116
	v_fma_f32 v98, v98, s31, 0.5
	v_fma_f32 v99, v99, s31, 0.5
	v_add_f32_e32 v90, 1.0, v90
	v_lshl_add_u64 v[114:115], v[114:115], 0, v[144:145]
	v_or3_b32 v106, v106, v111, v112
	v_or3_b32 v107, v107, v108, v109
	v_max_f32_e32 v98, 1.0, v98
	v_max_f32_e32 v99, 1.0, v99
	v_fma_f32 v100, v100, s31, 0.5
	v_fma_f32 v101, v101, s31, 0.5
	v_rcp_f32_e32 v90, v90
	global_store_dwordx2 v[114:115], v[106:107], off
	v_cvt_u32_f32_e32 v106, v98
	v_cvt_u32_f32_e32 v99, v99
	v_max_f32_e32 v100, 1.0, v100
	v_max_f32_e32 v101, 1.0, v101
	v_cvt_u32_f32_sdwa v100, v100 dst_sel:WORD_1 dst_unused:UNUSED_PAD src0_sel:DWORD
	v_cvt_u32_f32_sdwa v101, v101 dst_sel:BYTE_3 dst_unused:UNUSED_PAD src0_sel:DWORD
	v_mul_f32_e32 v102, v102, v160
	v_mul_f32_e32 v98, v103, v160
	v_mul_f32_e32 v103, v104, v160
	v_mul_f32_e32 v104, v105, v160
	v_fma_f32 v90, v90, s31, 0.5
	v_exp_f32_e32 v102, v102
	v_exp_f32_e32 v98, v98
	v_lshl_or_b32 v99, v99, 8, v106
	v_max_f32_e32 v90, 1.0, v90
	v_exp_f32_e32 v103, v103
	v_exp_f32_e32 v104, v104
	v_or3_b32 v99, v99, v100, v101
	v_mul_f32_e32 v94, v94, v159
	v_cvt_u32_f32_e32 v100, v90
	v_mul_f32_e32 v90, v95, v159
	v_mul_f32_e32 v91, v91, v159
	v_mul_f32_e32 v95, v96, v159
	v_mul_f32_e32 v92, v92, v159
	v_mul_f32_e32 v96, v97, v159
	v_mul_f32_e32 v93, v93, v159
	v_exp_f32_e32 v94, v94
	v_exp_f32_e32 v90, v90
	v_exp_f32_e32 v91, v91
	v_add_f32_e32 v102, 1.0, v102
	v_add_f32_e32 v98, 1.0, v98
	v_exp_f32_e32 v95, v95
	v_exp_f32_e32 v92, v92
	v_exp_f32_e32 v96, v96
	v_exp_f32_e32 v93, v93
	v_rcp_f32_e32 v102, v102
	v_rcp_f32_e32 v98, v98
	v_add_f32_e32 v103, 1.0, v103
	v_add_f32_e32 v104, 1.0, v104
	v_rcp_f32_e32 v103, v103
	v_rcp_f32_e32 v104, v104
	v_add_f32_e32 v94, 1.0, v94
	v_add_f32_e32 v90, 1.0, v90
	v_add_f32_e32 v91, 1.0, v91
	v_mul_f32_e32 v82, v82, v159
	v_mul_f32_e32 v83, v83, v159
	v_rcp_f32_e32 v94, v94
	v_rcp_f32_e32 v90, v90
	v_rcp_f32_e32 v91, v91
	v_add_f32_e32 v95, 1.0, v95
	v_add_f32_e32 v92, 1.0, v92
	v_add_f32_e32 v96, 1.0, v96
	v_add_f32_e32 v93, 1.0, v93
	v_mul_f32_e32 v84, v84, v159
	v_mul_f32_e32 v85, v85, v159
	v_fma_f32 v102, v102, s31, 0.5
	v_fma_f32 v98, v98, s31, 0.5
	v_rcp_f32_e32 v95, v95
	v_rcp_f32_e32 v92, v92
	v_rcp_f32_e32 v96, v96
	v_rcp_f32_e32 v93, v93
	v_exp_f32_e32 v82, v82
	v_exp_f32_e32 v83, v83
	v_max_f32_e32 v102, 1.0, v102
	v_max_f32_e32 v98, 1.0, v98
	v_fma_f32 v103, v103, s31, 0.5
	v_fma_f32 v104, v104, s31, 0.5
	v_exp_f32_e32 v84, v84
	v_exp_f32_e32 v85, v85
	v_cvt_u32_f32_e32 v102, v102
	v_cvt_u32_f32_e32 v98, v98
	v_max_f32_e32 v103, 1.0, v103
	v_max_f32_e32 v104, 1.0, v104
	v_cvt_u32_f32_sdwa v103, v103 dst_sel:WORD_1 dst_unused:UNUSED_PAD src0_sel:DWORD
	v_cvt_u32_f32_sdwa v104, v104 dst_sel:BYTE_3 dst_unused:UNUSED_PAD src0_sel:DWORD
	v_fma_f32 v94, v94, s31, 0.5
	v_fma_f32 v90, v90, s31, 0.5
	v_fma_f32 v91, v91, s31, 0.5
	v_mul_f32_e32 v74, v74, v158
	v_max_f32_e32 v94, 1.0, v94
	v_max_f32_e32 v90, 1.0, v90
	v_max_f32_e32 v91, 1.0, v91
	v_fma_f32 v95, v95, s31, 0.5
	v_fma_f32 v92, v92, s31, 0.5
	v_fma_f32 v96, v96, s31, 0.5
	v_fma_f32 v93, v93, s31, 0.5
	v_add_f32_e32 v82, 1.0, v82
	v_add_f32_e32 v83, 1.0, v83
	v_cvt_u32_f32_e32 v94, v94
	v_cvt_u32_f32_e32 v90, v90
	v_cvt_u32_f32_e32 v91, v91
	v_max_f32_e32 v95, 1.0, v95
	v_max_f32_e32 v92, 1.0, v92
	v_max_f32_e32 v96, 1.0, v96
	v_max_f32_e32 v93, 1.0, v93
	v_rcp_f32_e32 v82, v82
	v_rcp_f32_e32 v83, v83
	v_add_f32_e32 v84, 1.0, v84
	v_add_f32_e32 v85, 1.0, v85
	v_exp_f32_e32 v74, v74
	v_lshl_or_b32 v98, v98, 8, v102
	v_cvt_u32_f32_sdwa v95, v95 dst_sel:WORD_1 dst_unused:UNUSED_PAD src0_sel:DWORD
	v_cvt_u32_f32_sdwa v92, v92 dst_sel:WORD_1 dst_unused:UNUSED_PAD src0_sel:DWORD
	v_cvt_u32_f32_sdwa v96, v96 dst_sel:BYTE_3 dst_unused:UNUSED_PAD src0_sel:DWORD
	v_cvt_u32_f32_sdwa v93, v93 dst_sel:BYTE_3 dst_unused:UNUSED_PAD src0_sel:DWORD
	v_rcp_f32_e32 v84, v84
	v_rcp_f32_e32 v85, v85
	v_or3_b32 v98, v98, v103, v104
	global_store_dwordx2 v[114:115], v[98:99], off offset:128
	v_lshlrev_b64 v[98:99], 12, v[146:147]
	v_lshl_add_u64 v[98:99], s[12:13], 0, v[98:99]
	v_lshl_or_b32 v90, v90, 8, v94
	v_lshl_or_b32 v91, v91, 8, v100
	v_fma_f32 v82, v82, s31, 0.5
	v_fma_f32 v83, v83, s31, 0.5
	v_add_f32_e32 v74, 1.0, v74
	v_lshl_add_u64 v[98:99], v[98:99], 0, v[144:145]
	v_or3_b32 v90, v90, v95, v96
	v_or3_b32 v91, v91, v92, v93
	v_max_f32_e32 v82, 1.0, v82
	v_max_f32_e32 v83, 1.0, v83
	v_fma_f32 v84, v84, s31, 0.5
	v_fma_f32 v85, v85, s31, 0.5
	v_rcp_f32_e32 v74, v74
	global_store_dwordx2 v[98:99], v[90:91], off
	v_cvt_u32_f32_e32 v90, v82
	v_cvt_u32_f32_e32 v83, v83
	v_max_f32_e32 v84, 1.0, v84
	v_max_f32_e32 v85, 1.0, v85
	v_cvt_u32_f32_sdwa v84, v84 dst_sel:WORD_1 dst_unused:UNUSED_PAD src0_sel:DWORD
	v_cvt_u32_f32_sdwa v85, v85 dst_sel:BYTE_3 dst_unused:UNUSED_PAD src0_sel:DWORD
	v_mul_f32_e32 v86, v86, v159
	v_mul_f32_e32 v82, v87, v159
	v_mul_f32_e32 v87, v88, v159
	v_mul_f32_e32 v88, v89, v159
	v_fma_f32 v74, v74, s31, 0.5
	v_exp_f32_e32 v86, v86
	v_exp_f32_e32 v82, v82
	v_lshl_or_b32 v83, v83, 8, v90
	v_max_f32_e32 v74, 1.0, v74
	v_exp_f32_e32 v87, v87
	v_exp_f32_e32 v88, v88
	v_or3_b32 v83, v83, v84, v85
	v_mul_f32_e32 v78, v78, v158
	v_cvt_u32_f32_e32 v84, v74
	v_mul_f32_e32 v74, v79, v158
	v_mul_f32_e32 v75, v75, v158
	v_mul_f32_e32 v79, v80, v158
	v_mul_f32_e32 v76, v76, v158
	v_mul_f32_e32 v80, v81, v158
	v_mul_f32_e32 v77, v77, v158
	v_exp_f32_e32 v78, v78
	v_exp_f32_e32 v74, v74
	v_exp_f32_e32 v75, v75
	v_add_f32_e32 v86, 1.0, v86
	v_add_f32_e32 v82, 1.0, v82
	v_exp_f32_e32 v79, v79
	v_exp_f32_e32 v76, v76
	v_exp_f32_e32 v80, v80
	v_exp_f32_e32 v77, v77
	v_rcp_f32_e32 v86, v86
	v_rcp_f32_e32 v82, v82
	v_add_f32_e32 v87, 1.0, v87
	v_add_f32_e32 v88, 1.0, v88
	v_rcp_f32_e32 v87, v87
	v_rcp_f32_e32 v88, v88
	v_add_f32_e32 v78, 1.0, v78
	v_add_f32_e32 v74, 1.0, v74
	v_add_f32_e32 v75, 1.0, v75
	v_mul_f32_e32 v66, v66, v158
	v_mul_f32_e32 v67, v67, v158
	v_rcp_f32_e32 v78, v78
	v_rcp_f32_e32 v74, v74
	v_rcp_f32_e32 v75, v75
	v_add_f32_e32 v79, 1.0, v79
	v_add_f32_e32 v76, 1.0, v76
	v_add_f32_e32 v80, 1.0, v80
	v_add_f32_e32 v77, 1.0, v77
	v_mul_f32_e32 v68, v68, v158
	v_mul_f32_e32 v69, v69, v158
	v_fma_f32 v86, v86, s31, 0.5
	v_fma_f32 v82, v82, s31, 0.5
	v_rcp_f32_e32 v79, v79
	v_rcp_f32_e32 v76, v76
	v_rcp_f32_e32 v80, v80
	v_rcp_f32_e32 v77, v77
	v_exp_f32_e32 v66, v66
	v_exp_f32_e32 v67, v67
	v_max_f32_e32 v86, 1.0, v86
	v_max_f32_e32 v82, 1.0, v82
	v_fma_f32 v87, v87, s31, 0.5
	v_fma_f32 v88, v88, s31, 0.5
	v_exp_f32_e32 v68, v68
	v_exp_f32_e32 v69, v69
	v_cvt_u32_f32_e32 v86, v86
	v_cvt_u32_f32_e32 v82, v82
	v_max_f32_e32 v87, 1.0, v87
	v_max_f32_e32 v88, 1.0, v88
	v_cvt_u32_f32_sdwa v87, v87 dst_sel:WORD_1 dst_unused:UNUSED_PAD src0_sel:DWORD
	v_cvt_u32_f32_sdwa v88, v88 dst_sel:BYTE_3 dst_unused:UNUSED_PAD src0_sel:DWORD
	v_fma_f32 v78, v78, s31, 0.5
	v_fma_f32 v74, v74, s31, 0.5
	v_fma_f32 v75, v75, s31, 0.5
	v_mul_f32_e32 v58, v58, v157
	v_max_f32_e32 v78, 1.0, v78
	v_max_f32_e32 v74, 1.0, v74
	v_max_f32_e32 v75, 1.0, v75
	v_fma_f32 v79, v79, s31, 0.5
	v_fma_f32 v76, v76, s31, 0.5
	v_fma_f32 v80, v80, s31, 0.5
	v_fma_f32 v77, v77, s31, 0.5
	v_add_f32_e32 v66, 1.0, v66
	v_add_f32_e32 v67, 1.0, v67
	v_cvt_u32_f32_e32 v78, v78
	v_cvt_u32_f32_e32 v74, v74
	v_cvt_u32_f32_e32 v75, v75
	v_max_f32_e32 v79, 1.0, v79
	v_max_f32_e32 v76, 1.0, v76
	v_max_f32_e32 v80, 1.0, v80
	v_max_f32_e32 v77, 1.0, v77
	v_rcp_f32_e32 v66, v66
	v_rcp_f32_e32 v67, v67
	v_add_f32_e32 v68, 1.0, v68
	v_add_f32_e32 v69, 1.0, v69
	v_exp_f32_e32 v58, v58
	v_lshl_or_b32 v82, v82, 8, v86
	v_cvt_u32_f32_sdwa v79, v79 dst_sel:WORD_1 dst_unused:UNUSED_PAD src0_sel:DWORD
	v_cvt_u32_f32_sdwa v76, v76 dst_sel:WORD_1 dst_unused:UNUSED_PAD src0_sel:DWORD
	v_cvt_u32_f32_sdwa v80, v80 dst_sel:BYTE_3 dst_unused:UNUSED_PAD src0_sel:DWORD
	v_cvt_u32_f32_sdwa v77, v77 dst_sel:BYTE_3 dst_unused:UNUSED_PAD src0_sel:DWORD
	v_rcp_f32_e32 v68, v68
	v_rcp_f32_e32 v69, v69
	v_or3_b32 v82, v82, v87, v88
	global_store_dwordx2 v[98:99], v[82:83], off offset:128
	v_lshlrev_b64 v[82:83], 12, v[142:143]
	v_lshl_add_u64 v[82:83], s[12:13], 0, v[82:83]
	v_lshl_or_b32 v74, v74, 8, v78
	v_lshl_or_b32 v75, v75, 8, v84
	v_fma_f32 v66, v66, s31, 0.5
	v_fma_f32 v67, v67, s31, 0.5
	v_add_f32_e32 v58, 1.0, v58
	v_lshl_add_u64 v[82:83], v[82:83], 0, v[144:145]
	v_or3_b32 v74, v74, v79, v80
	v_or3_b32 v75, v75, v76, v77
	v_max_f32_e32 v66, 1.0, v66
	v_max_f32_e32 v67, 1.0, v67
	v_fma_f32 v68, v68, s31, 0.5
	v_fma_f32 v69, v69, s31, 0.5
	v_rcp_f32_e32 v58, v58
	global_store_dwordx2 v[82:83], v[74:75], off
	v_cvt_u32_f32_e32 v74, v66
	v_cvt_u32_f32_e32 v67, v67
	v_max_f32_e32 v68, 1.0, v68
	v_max_f32_e32 v69, 1.0, v69
	v_cvt_u32_f32_sdwa v68, v68 dst_sel:WORD_1 dst_unused:UNUSED_PAD src0_sel:DWORD
	v_cvt_u32_f32_sdwa v69, v69 dst_sel:BYTE_3 dst_unused:UNUSED_PAD src0_sel:DWORD
	v_fma_f32 v58, v58, s31, 0.5
	v_lshl_or_b32 v67, v67, 8, v74
	v_max_f32_e32 v58, 1.0, v58
	v_mul_f32_e32 v59, v59, v157
	v_or3_b32 v67, v67, v68, v69
	v_mul_f32_e32 v62, v62, v157
	v_cvt_u32_f32_e32 v68, v58
	v_mul_f32_e32 v58, v63, v157
	v_mul_f32_e32 v60, v60, v157
	v_mul_f32_e32 v61, v61, v157
	v_exp_f32_e32 v59, v59
	v_mul_f32_e32 v63, v64, v157
	v_mul_f32_e32 v64, v65, v157
	v_exp_f32_e32 v62, v62
	v_exp_f32_e32 v58, v58
	v_exp_f32_e32 v60, v60
	v_exp_f32_e32 v61, v61
	v_exp_f32_e32 v63, v63
	v_exp_f32_e32 v64, v64
	v_add_f32_e32 v59, 1.0, v59
	v_add_f32_e32 v62, 1.0, v62
	v_add_f32_e32 v58, 1.0, v58
	v_rcp_f32_e32 v59, v59
	v_add_f32_e32 v60, 1.0, v60
	v_add_f32_e32 v61, 1.0, v61
	v_mul_f32_e32 v50, v50, v157
	v_mul_f32_e32 v51, v51, v157
	v_rcp_f32_e32 v62, v62
	v_rcp_f32_e32 v58, v58
	v_add_f32_e32 v63, 1.0, v63
	v_rcp_f32_e32 v60, v60
	v_add_f32_e32 v64, 1.0, v64
	v_rcp_f32_e32 v61, v61
	v_mul_f32_e32 v52, v52, v157
	v_mul_f32_e32 v53, v53, v157
	v_rcp_f32_e32 v63, v63
	v_rcp_f32_e32 v64, v64
	v_exp_f32_e32 v50, v50
	v_exp_f32_e32 v51, v51
	v_exp_f32_e32 v52, v52
	v_exp_f32_e32 v53, v53
	v_fma_f32 v59, v59, s31, 0.5
	v_fma_f32 v62, v62, s31, 0.5
	v_fma_f32 v58, v58, s31, 0.5
	v_max_f32_e32 v59, 1.0, v59
	v_fma_f32 v60, v60, s31, 0.5
	v_fma_f32 v61, v61, s31, 0.5
	v_mul_f32_e32 v42, v42, v156
	v_max_f32_e32 v62, 1.0, v62
	v_max_f32_e32 v58, 1.0, v58
	v_cvt_u32_f32_e32 v59, v59
	v_fma_f32 v63, v63, s31, 0.5
	v_max_f32_e32 v60, 1.0, v60
	v_fma_f32 v64, v64, s31, 0.5
	v_max_f32_e32 v61, 1.0, v61
	v_add_f32_e32 v50, 1.0, v50
	v_add_f32_e32 v51, 1.0, v51
	v_cvt_u32_f32_e32 v62, v62
	v_cvt_u32_f32_e32 v58, v58
	v_max_f32_e32 v63, 1.0, v63
	v_cvt_u32_f32_sdwa v60, v60 dst_sel:WORD_1 dst_unused:UNUSED_PAD src0_sel:DWORD
	v_max_f32_e32 v64, 1.0, v64
	v_cvt_u32_f32_sdwa v61, v61 dst_sel:BYTE_3 dst_unused:UNUSED_PAD src0_sel:DWORD
	v_rcp_f32_e32 v50, v50
	v_rcp_f32_e32 v51, v51
	v_add_f32_e32 v52, 1.0, v52
	v_add_f32_e32 v53, 1.0, v53
	v_exp_f32_e32 v42, v42
	v_cvt_u32_f32_sdwa v63, v63 dst_sel:WORD_1 dst_unused:UNUSED_PAD src0_sel:DWORD
	v_cvt_u32_f32_sdwa v64, v64 dst_sel:BYTE_3 dst_unused:UNUSED_PAD src0_sel:DWORD
	v_rcp_f32_e32 v52, v52
	v_rcp_f32_e32 v53, v53
	v_lshl_or_b32 v59, v59, 8, v68
	v_lshl_or_b32 v58, v58, 8, v62
	v_or3_b32 v59, v59, v60, v61
	v_add_co_u32_e32 v60, vcc, s5, v140
	v_fma_f32 v50, v50, s31, 0.5
	v_fma_f32 v51, v51, s31, 0.5
	v_add_f32_e32 v42, 1.0, v42
	v_or3_b32 v58, v58, v63, v64
	v_addc_co_u32_e32 v61, vcc, 0, v141, vcc
	v_max_f32_e32 v50, 1.0, v50
	v_max_f32_e32 v51, 1.0, v51
	v_fma_f32 v52, v52, s31, 0.5
	v_fma_f32 v53, v53, s31, 0.5
	v_rcp_f32_e32 v42, v42
	global_store_dwordx2 v[60:61], v[58:59], off
	v_cvt_u32_f32_e32 v58, v50
	v_cvt_u32_f32_e32 v51, v51
	v_max_f32_e32 v52, 1.0, v52
	v_max_f32_e32 v53, 1.0, v53
	v_cvt_u32_f32_sdwa v52, v52 dst_sel:WORD_1 dst_unused:UNUSED_PAD src0_sel:DWORD
	v_cvt_u32_f32_sdwa v53, v53 dst_sel:BYTE_3 dst_unused:UNUSED_PAD src0_sel:DWORD
	v_fma_f32 v42, v42, s31, 0.5
	v_lshl_or_b32 v51, v51, 8, v58
	v_max_f32_e32 v42, 1.0, v42
	v_mul_f32_e32 v43, v43, v156
	v_or3_b32 v51, v51, v52, v53
	v_mul_f32_e32 v46, v46, v156
	v_cvt_u32_f32_e32 v52, v42
	v_mul_f32_e32 v42, v47, v156
	v_mul_f32_e32 v44, v44, v156
	v_mul_f32_e32 v45, v45, v156
	v_exp_f32_e32 v43, v43
	v_mul_f32_e32 v47, v48, v156
	v_mul_f32_e32 v48, v49, v156
	v_exp_f32_e32 v46, v46
	v_exp_f32_e32 v42, v42
	v_exp_f32_e32 v44, v44
	v_exp_f32_e32 v45, v45
	v_exp_f32_e32 v47, v47
	v_exp_f32_e32 v48, v48
	v_add_f32_e32 v43, 1.0, v43
	v_add_f32_e32 v46, 1.0, v46
	v_add_f32_e32 v42, 1.0, v42
	v_rcp_f32_e32 v43, v43
	v_add_f32_e32 v44, 1.0, v44
	v_add_f32_e32 v45, 1.0, v45
	v_mul_f32_e32 v34, v34, v156
	v_mul_f32_e32 v35, v35, v156
	v_rcp_f32_e32 v46, v46
	v_rcp_f32_e32 v42, v42
	v_add_f32_e32 v47, 1.0, v47
	v_rcp_f32_e32 v44, v44
	v_add_f32_e32 v48, 1.0, v48
	v_rcp_f32_e32 v45, v45
	v_mul_f32_e32 v36, v36, v156
	v_mul_f32_e32 v37, v37, v156
	v_rcp_f32_e32 v47, v47
	v_rcp_f32_e32 v48, v48
	v_exp_f32_e32 v34, v34
	v_exp_f32_e32 v35, v35
	v_exp_f32_e32 v36, v36
	v_exp_f32_e32 v37, v37
	v_fma_f32 v43, v43, s31, 0.5
	v_fma_f32 v46, v46, s31, 0.5
	v_fma_f32 v42, v42, s31, 0.5
	v_max_f32_e32 v43, 1.0, v43
	v_fma_f32 v44, v44, s31, 0.5
	v_fma_f32 v45, v45, s31, 0.5
	v_mul_f32_e32 v26, v26, v155
	v_max_f32_e32 v46, 1.0, v46
	v_max_f32_e32 v42, 1.0, v42
	v_cvt_u32_f32_e32 v43, v43
	v_fma_f32 v47, v47, s31, 0.5
	v_max_f32_e32 v44, 1.0, v44
	v_fma_f32 v48, v48, s31, 0.5
	v_max_f32_e32 v45, 1.0, v45
	v_add_f32_e32 v34, 1.0, v34
	v_add_f32_e32 v35, 1.0, v35
	v_cvt_u32_f32_e32 v46, v46
	v_cvt_u32_f32_e32 v42, v42
	v_max_f32_e32 v47, 1.0, v47
	v_cvt_u32_f32_sdwa v44, v44 dst_sel:WORD_1 dst_unused:UNUSED_PAD src0_sel:DWORD
	v_max_f32_e32 v48, 1.0, v48
	v_cvt_u32_f32_sdwa v45, v45 dst_sel:BYTE_3 dst_unused:UNUSED_PAD src0_sel:DWORD
	v_rcp_f32_e32 v34, v34
	v_rcp_f32_e32 v35, v35
	v_add_f32_e32 v36, 1.0, v36
	v_add_f32_e32 v37, 1.0, v37
	v_exp_f32_e32 v26, v26
	v_cvt_u32_f32_sdwa v47, v47 dst_sel:WORD_1 dst_unused:UNUSED_PAD src0_sel:DWORD
	v_cvt_u32_f32_sdwa v48, v48 dst_sel:BYTE_3 dst_unused:UNUSED_PAD src0_sel:DWORD
	v_rcp_f32_e32 v36, v36
	v_rcp_f32_e32 v37, v37
	v_lshl_or_b32 v43, v43, 8, v52
	s_mov_b32 s5, 0x90000
	v_lshl_or_b32 v42, v42, 8, v46
	v_or3_b32 v43, v43, v44, v45
	v_add_co_u32_e32 v44, vcc, s5, v140
	v_fma_f32 v34, v34, s31, 0.5
	v_fma_f32 v35, v35, s31, 0.5
	v_add_f32_e32 v26, 1.0, v26
	v_or3_b32 v42, v42, v47, v48
	v_addc_co_u32_e32 v45, vcc, 0, v141, vcc
	v_max_f32_e32 v34, 1.0, v34
	v_max_f32_e32 v35, 1.0, v35
	v_fma_f32 v36, v36, s31, 0.5
	v_fma_f32 v37, v37, s31, 0.5
	v_rcp_f32_e32 v26, v26
	global_store_dwordx2 v[44:45], v[42:43], off
	v_cvt_u32_f32_e32 v42, v34
	v_cvt_u32_f32_e32 v35, v35
	v_max_f32_e32 v36, 1.0, v36
	v_max_f32_e32 v37, 1.0, v37
	v_cvt_u32_f32_sdwa v36, v36 dst_sel:WORD_1 dst_unused:UNUSED_PAD src0_sel:DWORD
	v_cvt_u32_f32_sdwa v37, v37 dst_sel:BYTE_3 dst_unused:UNUSED_PAD src0_sel:DWORD
	v_fma_f32 v26, v26, s31, 0.5
	v_lshl_or_b32 v35, v35, 8, v42
	v_max_f32_e32 v26, 1.0, v26
	v_mul_f32_e32 v27, v27, v155
	v_or3_b32 v35, v35, v36, v37
	v_mul_f32_e32 v30, v30, v155
	v_cvt_u32_f32_e32 v36, v26
	v_mul_f32_e32 v26, v31, v155
	v_mul_f32_e32 v28, v28, v155
	v_mul_f32_e32 v29, v29, v155
	v_exp_f32_e32 v27, v27
	v_mul_f32_e32 v31, v32, v155
	v_mul_f32_e32 v32, v33, v155
	v_exp_f32_e32 v30, v30
	v_exp_f32_e32 v26, v26
	v_exp_f32_e32 v28, v28
	v_exp_f32_e32 v29, v29
	v_exp_f32_e32 v31, v31
	v_exp_f32_e32 v32, v32
	v_add_f32_e32 v27, 1.0, v27
	v_add_f32_e32 v30, 1.0, v30
	v_add_f32_e32 v26, 1.0, v26
	v_rcp_f32_e32 v27, v27
	v_add_f32_e32 v28, 1.0, v28
	v_add_f32_e32 v29, 1.0, v29
	v_mul_f32_e32 v18, v18, v155
	v_mul_f32_e32 v19, v19, v155
	v_rcp_f32_e32 v30, v30
	v_rcp_f32_e32 v26, v26
	v_add_f32_e32 v31, 1.0, v31
	v_rcp_f32_e32 v28, v28
	v_add_f32_e32 v32, 1.0, v32
	v_rcp_f32_e32 v29, v29
	v_mul_f32_e32 v20, v20, v155
	v_mul_f32_e32 v21, v21, v155
	v_rcp_f32_e32 v31, v31
	v_rcp_f32_e32 v32, v32
	v_exp_f32_e32 v18, v18
	v_exp_f32_e32 v19, v19
	v_exp_f32_e32 v20, v20
	v_exp_f32_e32 v21, v21
	v_fma_f32 v27, v27, s31, 0.5
	v_fma_f32 v30, v30, s31, 0.5
	v_fma_f32 v26, v26, s31, 0.5
	v_max_f32_e32 v27, 1.0, v27
	v_fma_f32 v28, v28, s31, 0.5
	v_fma_f32 v29, v29, s31, 0.5
	v_mul_f32_e32 v8, v8, v154
	v_max_f32_e32 v30, 1.0, v30
	v_max_f32_e32 v26, 1.0, v26
	v_cvt_u32_f32_e32 v27, v27
	v_fma_f32 v31, v31, s31, 0.5
	v_max_f32_e32 v28, 1.0, v28
	v_fma_f32 v32, v32, s31, 0.5
	v_max_f32_e32 v29, 1.0, v29
	v_add_f32_e32 v18, 1.0, v18
	v_add_f32_e32 v19, 1.0, v19
	v_cvt_u32_f32_e32 v30, v30
	v_cvt_u32_f32_e32 v26, v26
	v_max_f32_e32 v31, 1.0, v31
	v_cvt_u32_f32_sdwa v28, v28 dst_sel:WORD_1 dst_unused:UNUSED_PAD src0_sel:DWORD
	v_max_f32_e32 v32, 1.0, v32
	v_cvt_u32_f32_sdwa v29, v29 dst_sel:BYTE_3 dst_unused:UNUSED_PAD src0_sel:DWORD
	v_rcp_f32_e32 v18, v18
	v_rcp_f32_e32 v19, v19
	v_add_f32_e32 v20, 1.0, v20
	v_add_f32_e32 v21, 1.0, v21
	v_exp_f32_e32 v8, v8
	v_cvt_u32_f32_sdwa v31, v31 dst_sel:WORD_1 dst_unused:UNUSED_PAD src0_sel:DWORD
	v_cvt_u32_f32_sdwa v32, v32 dst_sel:BYTE_3 dst_unused:UNUSED_PAD src0_sel:DWORD
	v_rcp_f32_e32 v20, v20
	v_rcp_f32_e32 v21, v21
	v_lshl_or_b32 v27, v27, 8, v36
	s_mov_b32 s5, 0xa0000
	v_lshl_or_b32 v26, v26, 8, v30
	v_or3_b32 v27, v27, v28, v29
	v_add_co_u32_e32 v28, vcc, s5, v140
	v_fma_f32 v18, v18, s31, 0.5
	v_fma_f32 v19, v19, s31, 0.5
	v_add_f32_e32 v8, 1.0, v8
	v_or3_b32 v26, v26, v31, v32
	v_addc_co_u32_e32 v29, vcc, 0, v141, vcc
	v_max_f32_e32 v18, 1.0, v18
	v_max_f32_e32 v19, 1.0, v19
	v_fma_f32 v20, v20, s31, 0.5
	v_fma_f32 v21, v21, s31, 0.5
	v_rcp_f32_e32 v8, v8
	global_store_dwordx2 v[28:29], v[26:27], off
	v_cvt_u32_f32_e32 v26, v18
	v_cvt_u32_f32_e32 v19, v19
	v_max_f32_e32 v20, 1.0, v20
	v_max_f32_e32 v21, 1.0, v21
	v_cvt_u32_f32_sdwa v20, v20 dst_sel:WORD_1 dst_unused:UNUSED_PAD src0_sel:DWORD
	v_cvt_u32_f32_sdwa v21, v21 dst_sel:BYTE_3 dst_unused:UNUSED_PAD src0_sel:DWORD
	v_fma_f32 v8, v8, s31, 0.5
	v_lshl_or_b32 v19, v19, 8, v26
	v_max_f32_e32 v8, 1.0, v8
	v_mul_f32_e32 v9, v9, v154
	v_or3_b32 v19, v19, v20, v21
	v_mul_f32_e32 v12, v12, v154
	v_cvt_u32_f32_e32 v20, v8
	v_mul_f32_e32 v8, v13, v154
	v_mul_f32_e32 v10, v10, v154
	v_mul_f32_e32 v11, v11, v154
	v_exp_f32_e32 v9, v9
	v_mul_f32_e32 v13, v14, v154
	v_mul_f32_e32 v14, v15, v154
	v_exp_f32_e32 v12, v12
	v_exp_f32_e32 v8, v8
	v_exp_f32_e32 v10, v10
	v_exp_f32_e32 v11, v11
	v_exp_f32_e32 v13, v13
	v_exp_f32_e32 v14, v14
	v_add_f32_e32 v9, 1.0, v9
	v_add_f32_e32 v12, 1.0, v12
	v_add_f32_e32 v8, 1.0, v8
	v_rcp_f32_e32 v9, v9
	v_add_f32_e32 v10, 1.0, v10
	v_add_f32_e32 v11, 1.0, v11
	v_mul_f32_e32 v0, v0, v154
	v_rcp_f32_e32 v12, v12
	v_rcp_f32_e32 v8, v8
	v_add_f32_e32 v13, 1.0, v13
	v_rcp_f32_e32 v10, v10
	v_add_f32_e32 v14, 1.0, v14
	v_rcp_f32_e32 v11, v11
	v_rcp_f32_e32 v13, v13
	v_rcp_f32_e32 v14, v14
	v_exp_f32_e32 v0, v0
	v_fma_f32 v9, v9, s31, 0.5
	v_fma_f32 v12, v12, s31, 0.5
	v_fma_f32 v8, v8, s31, 0.5
	v_max_f32_e32 v9, 1.0, v9
	v_fma_f32 v10, v10, s31, 0.5
	v_fma_f32 v11, v11, s31, 0.5
	v_max_f32_e32 v12, 1.0, v12
	v_max_f32_e32 v8, 1.0, v8
	v_cvt_u32_f32_e32 v9, v9
	v_fma_f32 v13, v13, s31, 0.5
	v_max_f32_e32 v10, 1.0, v10
	v_fma_f32 v14, v14, s31, 0.5
	v_max_f32_e32 v11, 1.0, v11
	v_add_f32_e32 v0, 1.0, v0
	v_cvt_u32_f32_e32 v12, v12
	v_cvt_u32_f32_e32 v8, v8
	v_max_f32_e32 v13, 1.0, v13
	v_cvt_u32_f32_sdwa v10, v10 dst_sel:WORD_1 dst_unused:UNUSED_PAD src0_sel:DWORD
	v_max_f32_e32 v14, 1.0, v14
	v_cvt_u32_f32_sdwa v11, v11 dst_sel:BYTE_3 dst_unused:UNUSED_PAD src0_sel:DWORD
	v_rcp_f32_e32 v0, v0
	v_cvt_u32_f32_sdwa v13, v13 dst_sel:WORD_1 dst_unused:UNUSED_PAD src0_sel:DWORD
	v_cvt_u32_f32_sdwa v14, v14 dst_sel:BYTE_3 dst_unused:UNUSED_PAD src0_sel:DWORD
	v_mul_f32_e32 v70, v70, v158
	v_mul_f32_e32 v66, v71, v158
	v_mul_f32_e32 v71, v72, v158
	v_mul_f32_e32 v72, v73, v158
	v_mul_f32_e32 v54, v54, v157
	v_mul_f32_e32 v50, v55, v157
	v_lshl_or_b32 v9, v9, 8, v20
	s_mov_b32 s5, 0xb0000
	v_exp_f32_e32 v70, v70
	v_exp_f32_e32 v66, v66
	v_mul_f32_e32 v55, v56, v157
	v_mul_f32_e32 v56, v57, v157
	v_mul_f32_e32 v38, v38, v156
	v_mul_f32_e32 v34, v39, v156
	v_lshl_or_b32 v8, v8, 8, v12
	v_or3_b32 v9, v9, v10, v11
	v_add_co_u32_e32 v10, vcc, s5, v140
	v_fma_f32 v0, v0, s31, 0.5
	v_exp_f32_e32 v71, v71
	v_exp_f32_e32 v72, v72
	v_exp_f32_e32 v54, v54
	v_exp_f32_e32 v50, v50
	v_mul_f32_e32 v39, v40, v156
	v_mul_f32_e32 v40, v41, v156
	v_mul_f32_e32 v22, v22, v155
	v_mul_f32_e32 v18, v23, v155
	v_or3_b32 v8, v8, v13, v14
	v_addc_co_u32_e32 v11, vcc, 0, v141, vcc
	v_max_f32_e32 v0, 1.0, v0
	v_exp_f32_e32 v55, v55
	v_exp_f32_e32 v56, v56
	v_exp_f32_e32 v38, v38
	v_exp_f32_e32 v34, v34
	v_mul_f32_e32 v23, v24, v155
	v_mul_f32_e32 v24, v25, v155
	global_store_dwordx2 v[10:11], v[8:9], off
	v_mul_f32_e32 v4, v4, v154
	v_cvt_u32_f32_e32 v8, v0
	v_mul_f32_e32 v0, v5, v154
	v_mul_f32_e32 v1, v1, v154
	v_exp_f32_e32 v39, v39
	v_exp_f32_e32 v40, v40
	v_exp_f32_e32 v22, v22
	v_exp_f32_e32 v18, v18
	v_mul_f32_e32 v5, v6, v154
	v_mul_f32_e32 v2, v2, v154
	v_mul_f32_e32 v6, v7, v154
	v_mul_f32_e32 v3, v3, v154
	v_add_f32_e32 v70, 1.0, v70
	v_add_f32_e32 v66, 1.0, v66
	v_exp_f32_e32 v23, v23
	v_exp_f32_e32 v24, v24
	v_exp_f32_e32 v4, v4
	v_exp_f32_e32 v0, v0
	v_exp_f32_e32 v1, v1
	v_rcp_f32_e32 v70, v70
	v_rcp_f32_e32 v66, v66
	v_add_f32_e32 v71, 1.0, v71
	v_add_f32_e32 v72, 1.0, v72
	v_add_f32_e32 v54, 1.0, v54
	v_add_f32_e32 v50, 1.0, v50
	v_exp_f32_e32 v5, v5
	v_exp_f32_e32 v2, v2
	v_exp_f32_e32 v6, v6
	v_exp_f32_e32 v3, v3
	v_rcp_f32_e32 v71, v71
	v_rcp_f32_e32 v72, v72
	v_rcp_f32_e32 v54, v54
	v_rcp_f32_e32 v50, v50
	v_add_f32_e32 v55, 1.0, v55
	v_add_f32_e32 v56, 1.0, v56
	v_add_f32_e32 v38, 1.0, v38
	v_add_f32_e32 v34, 1.0, v34
	v_rcp_f32_e32 v55, v55
	v_rcp_f32_e32 v56, v56
	v_rcp_f32_e32 v38, v38
	v_rcp_f32_e32 v34, v34
	v_add_f32_e32 v39, 1.0, v39
	v_add_f32_e32 v40, 1.0, v40
	v_add_f32_e32 v22, 1.0, v22
	v_add_f32_e32 v18, 1.0, v18
	v_rcp_f32_e32 v39, v39
	v_rcp_f32_e32 v40, v40
	v_rcp_f32_e32 v22, v22
	v_rcp_f32_e32 v18, v18
	v_add_f32_e32 v23, 1.0, v23
	v_add_f32_e32 v24, 1.0, v24
	v_add_f32_e32 v4, 1.0, v4
	v_add_f32_e32 v0, 1.0, v0
	v_add_f32_e32 v1, 1.0, v1
	v_fma_f32 v70, v70, s31, 0.5
	v_fma_f32 v66, v66, s31, 0.5
	v_rcp_f32_e32 v23, v23
	v_rcp_f32_e32 v24, v24
	v_rcp_f32_e32 v4, v4
	v_rcp_f32_e32 v0, v0
	v_rcp_f32_e32 v1, v1
	v_add_f32_e32 v5, 1.0, v5
	v_add_f32_e32 v2, 1.0, v2
	v_add_f32_e32 v6, 1.0, v6
	v_add_f32_e32 v3, 1.0, v3
	v_max_f32_e32 v70, 1.0, v70
	v_max_f32_e32 v66, 1.0, v66
	v_fma_f32 v71, v71, s31, 0.5
	v_fma_f32 v72, v72, s31, 0.5
	v_fma_f32 v54, v54, s31, 0.5
	v_fma_f32 v50, v50, s31, 0.5
	v_rcp_f32_e32 v5, v5
	v_rcp_f32_e32 v2, v2
	v_rcp_f32_e32 v6, v6
	v_rcp_f32_e32 v3, v3
	v_cvt_u32_f32_e32 v70, v70
	v_cvt_u32_f32_e32 v66, v66
	v_max_f32_e32 v71, 1.0, v71
	v_max_f32_e32 v72, 1.0, v72
	v_max_f32_e32 v54, 1.0, v54
	v_max_f32_e32 v50, 1.0, v50
	v_fma_f32 v55, v55, s31, 0.5
	v_fma_f32 v56, v56, s31, 0.5
	v_fma_f32 v38, v38, s31, 0.5
	v_fma_f32 v34, v34, s31, 0.5
	v_cvt_u32_f32_sdwa v71, v71 dst_sel:WORD_1 dst_unused:UNUSED_PAD src0_sel:DWORD
	v_cvt_u32_f32_sdwa v72, v72 dst_sel:BYTE_3 dst_unused:UNUSED_PAD src0_sel:DWORD
	v_cvt_u32_f32_e32 v54, v54
	v_cvt_u32_f32_e32 v50, v50
	v_max_f32_e32 v55, 1.0, v55
	v_max_f32_e32 v56, 1.0, v56
	v_max_f32_e32 v38, 1.0, v38
	v_max_f32_e32 v34, 1.0, v34
	v_fma_f32 v39, v39, s31, 0.5
	v_fma_f32 v40, v40, s31, 0.5
	v_fma_f32 v22, v22, s31, 0.5
	v_fma_f32 v18, v18, s31, 0.5
	v_cvt_u32_f32_sdwa v55, v55 dst_sel:WORD_1 dst_unused:UNUSED_PAD src0_sel:DWORD
	v_cvt_u32_f32_sdwa v56, v56 dst_sel:BYTE_3 dst_unused:UNUSED_PAD src0_sel:DWORD
	v_cvt_u32_f32_e32 v38, v38
	v_cvt_u32_f32_e32 v34, v34
	v_max_f32_e32 v39, 1.0, v39
	v_max_f32_e32 v40, 1.0, v40
	v_max_f32_e32 v22, 1.0, v22
	v_max_f32_e32 v18, 1.0, v18
	v_fma_f32 v23, v23, s31, 0.5
	v_fma_f32 v24, v24, s31, 0.5
	v_fma_f32 v4, v4, s31, 0.5
	v_fma_f32 v0, v0, s31, 0.5
	v_fma_f32 v1, v1, s31, 0.5
	v_cvt_u32_f32_sdwa v39, v39 dst_sel:WORD_1 dst_unused:UNUSED_PAD src0_sel:DWORD
	v_cvt_u32_f32_sdwa v40, v40 dst_sel:BYTE_3 dst_unused:UNUSED_PAD src0_sel:DWORD
	v_cvt_u32_f32_e32 v22, v22
	v_cvt_u32_f32_e32 v18, v18
	v_max_f32_e32 v23, 1.0, v23
	v_max_f32_e32 v24, 1.0, v24
	v_max_f32_e32 v4, 1.0, v4
	v_max_f32_e32 v0, 1.0, v0
	v_max_f32_e32 v1, 1.0, v1
	v_fma_f32 v5, v5, s31, 0.5
	v_fma_f32 v2, v2, s31, 0.5
	v_fma_f32 v6, v6, s31, 0.5
	v_fma_f32 v3, v3, s31, 0.5
	v_lshl_or_b32 v66, v66, 8, v70
	v_cvt_u32_f32_sdwa v23, v23 dst_sel:WORD_1 dst_unused:UNUSED_PAD src0_sel:DWORD
	v_cvt_u32_f32_sdwa v24, v24 dst_sel:BYTE_3 dst_unused:UNUSED_PAD src0_sel:DWORD
	v_cvt_u32_f32_e32 v4, v4
	v_cvt_u32_f32_e32 v0, v0
	v_cvt_u32_f32_e32 v1, v1
	v_max_f32_e32 v5, 1.0, v5
	v_max_f32_e32 v2, 1.0, v2
	v_max_f32_e32 v6, 1.0, v6
	v_max_f32_e32 v3, 1.0, v3
	v_or3_b32 v66, v66, v71, v72
	s_mov_b64 s[12:13], 0x80000
	v_lshl_or_b32 v50, v50, 8, v54
	v_cvt_u32_f32_sdwa v5, v5 dst_sel:WORD_1 dst_unused:UNUSED_PAD src0_sel:DWORD
	v_cvt_u32_f32_sdwa v2, v2 dst_sel:WORD_1 dst_unused:UNUSED_PAD src0_sel:DWORD
	v_cvt_u32_f32_sdwa v6, v6 dst_sel:BYTE_3 dst_unused:UNUSED_PAD src0_sel:DWORD
	v_cvt_u32_f32_sdwa v3, v3 dst_sel:BYTE_3 dst_unused:UNUSED_PAD src0_sel:DWORD
	global_store_dwordx2 v[82:83], v[66:67], off offset:128
	v_lshl_add_u64 v[66:67], v[140:141], 0, s[12:13]
	v_or3_b32 v50, v50, v55, v56
	s_mov_b64 s[12:13], 0x90000
	v_lshl_or_b32 v34, v34, 8, v38
	global_store_dwordx2 v[66:67], v[50:51], off offset:128
	v_lshl_add_u64 v[50:51], v[140:141], 0, s[12:13]
	v_or3_b32 v34, v34, v39, v40
	s_mov_b64 s[12:13], 0xa0000
	v_lshl_or_b32 v18, v18, 8, v22
	global_store_dwordx2 v[50:51], v[34:35], off offset:128
	v_lshl_add_u64 v[34:35], v[140:141], 0, s[12:13]
	v_or3_b32 v18, v18, v23, v24
	s_mov_b64 s[12:13], 0xb0000
	v_lshl_or_b32 v0, v0, 8, v4
	v_lshl_or_b32 v1, v1, 8, v8
	global_store_dwordx2 v[34:35], v[18:19], off offset:128
	v_lshl_add_u64 v[18:19], v[140:141], 0, s[12:13]
	v_or3_b32 v0, v0, v5, v6
	v_or3_b32 v1, v1, v2, v3
	s_and_b64 vcc, exec, s[0:1]
	s_mov_b64 s[12:13], s[8:9]
	global_store_dwordx2 v[18:19], v[0:1], off offset:128
	s_cbranch_vccz .LBB0_955
	s_waitcnt vmcnt(0)
	s_cmpk_gt_u32 s34, 0xff
	s_cbranch_scc1 .LBB0_966
	s_barrier
